# v011 + nt on phase-0 transposed-weight image stores (write-once, read much later)
# speedup vs baseline: 1.0112x; 1.0060x over previous
; #define LAS __attribute__((address_space(3)))
; __device__ __forceinline__ void transpose_item(const float* W, int ldw, bf16_t* WT, int ldt, int koff, int k0, int nsrc, int ndst, LAS float* scr, int lane) {
;     const float* src = W + (size_t)k0 * ldw + nsrc + lane;
; #pragma unroll 32
;     for (int kk = 0; kk < 64; ++kk) scr[kk * 65 + lane] = src[(size_t)kk * ldw];
; __device__ __forceinline__ void phase0(const Args& a, LAS unsigned char* lds, int bid, int G) {
;     ...
;         if (r < I_IN) { const int kb = r / 384, nb = r - kb * 384; transpose_item(a.w_in, PC, WinT, LDP, 0, 64 * kb, proj_src_col(64 * nb), 64 * nb, scr, lane); continue; } r -= I_IN;
.LBB0_20:
	s_lshl_b32 s9, s77, 6
	s_mul_i32 s10, s77, 0x600000
	s_mul_hi_i32 s9, s9, 0x18000
	s_waitcnt lgkmcnt(0)
	s_add_u32 s10, s40, s10
	s_addc_u32 s11, s41, s9
	s_ashr_i32 s9, s8, 31
	s_lshl_b64 s[8:9], s[8:9], 2
	s_add_u32 s8, s10, s8
	s_addc_u32 s9, s11, s9
	v_lshl_add_u64 v[62:63], s[8:9], 0, v[2:3]
	v_add_co_u32_e32 v4, vcc, s69, v62
	global_load_dword v158, v2, s[8:9] nt
	s_nop 0
	v_addc_co_u32_e32 v5, vcc, 0, v63, vcc
	v_add_co_u32_e32 v6, vcc, s75, v62
	s_mov_b32 s8, 0x108000
	s_nop 0
	v_addc_co_u32_e32 v7, vcc, 0, v63, vcc
	v_add_co_u32_e32 v8, vcc, s88, v62
	s_movk_i32 s10, 0x1000
	s_nop 0
	v_addc_co_u32_e32 v9, vcc, 0, v63, vcc
	v_add_co_u32_e32 v10, vcc, s89, v62
	s_nop 1
	v_addc_co_u32_e32 v11, vcc, 0, v63, vcc
	v_add_co_u32_e32 v12, vcc, s93, v62
	s_nop 1
	v_addc_co_u32_e32 v13, vcc, 0, v63, vcc
	v_add_co_u32_e32 v14, vcc, s27, v62
	s_nop 1
	v_addc_co_u32_e32 v15, vcc, 0, v63, vcc
	v_add_co_u32_e32 v16, vcc, s55, v62
	s_nop 1
	v_addc_co_u32_e32 v17, vcc, 0, v63, vcc
	v_add_co_u32_e32 v18, vcc, s19, v62
	s_nop 1
	v_addc_co_u32_e32 v19, vcc, 0, v63, vcc
	v_add_co_u32_e32 v20, vcc, s35, v62
	s_nop 1
	v_addc_co_u32_e32 v21, vcc, 0, v63, vcc
	v_add_co_u32_e32 v22, vcc, s70, v62
	s_nop 1
	v_addc_co_u32_e32 v23, vcc, 0, v63, vcc
	v_add_co_u32_e32 v24, vcc, s8, v62
	s_mov_b32 s8, 0x120000
	s_nop 0
	v_addc_co_u32_e32 v25, vcc, 0, v63, vcc
	v_add_co_u32_e32 v26, vcc, s8, v62
	s_mov_b32 s8, 0x138000
	s_nop 0
	v_addc_co_u32_e32 v27, vcc, 0, v63, vcc
	v_add_co_u32_e32 v28, vcc, s8, v62
	s_mov_b32 s8, 0x150000
	s_nop 0
	v_addc_co_u32_e32 v29, vcc, 0, v63, vcc
	v_add_co_u32_e32 v30, vcc, s8, v62
	s_mov_b32 s8, 0x168000
	s_nop 0
	v_addc_co_u32_e32 v31, vcc, 0, v63, vcc
	v_add_co_u32_e32 v32, vcc, s8, v62
	s_mov_b32 s8, 0x180000
	s_nop 0
	v_addc_co_u32_e32 v33, vcc, 0, v63, vcc
	v_add_co_u32_e32 v34, vcc, s8, v62
	s_mov_b32 s8, 0x198000
	s_nop 0
	v_addc_co_u32_e32 v35, vcc, 0, v63, vcc
	v_add_co_u32_e32 v36, vcc, s8, v62
	s_mov_b32 s8, 0x1b0000
	s_nop 0
	v_addc_co_u32_e32 v37, vcc, 0, v63, vcc
	v_add_co_u32_e32 v38, vcc, s8, v62
	s_mov_b32 s8, 0x1c8000
	s_nop 0
	v_addc_co_u32_e32 v39, vcc, 0, v63, vcc
	v_add_co_u32_e32 v40, vcc, s8, v62
	s_mov_b32 s8, 0x1e0000
	s_nop 0
	v_addc_co_u32_e32 v41, vcc, 0, v63, vcc
	v_add_co_u32_e32 v42, vcc, s8, v62
	s_mov_b32 s8, 0x1f8000
	s_nop 0
	v_addc_co_u32_e32 v43, vcc, 0, v63, vcc
	v_add_co_u32_e32 v44, vcc, s8, v62
	s_mov_b32 s8, 0x210000
	s_nop 0
	v_addc_co_u32_e32 v45, vcc, 0, v63, vcc
	v_add_co_u32_e32 v46, vcc, s8, v62
	s_mov_b32 s8, 0x228000
	s_nop 0
	v_addc_co_u32_e32 v47, vcc, 0, v63, vcc
	v_add_co_u32_e32 v48, vcc, s8, v62
	s_mov_b32 s8, 0x240000
	s_nop 0
	v_addc_co_u32_e32 v49, vcc, 0, v63, vcc
	v_add_co_u32_e32 v50, vcc, s8, v62
	s_mov_b32 s8, 0x258000
	s_nop 0
	v_addc_co_u32_e32 v51, vcc, 0, v63, vcc
	v_add_co_u32_e32 v52, vcc, s8, v62
	s_mov_b32 s8, 0x270000
	s_nop 0
	v_addc_co_u32_e32 v53, vcc, 0, v63, vcc
	v_add_co_u32_e32 v54, vcc, s8, v62
	s_mov_b32 s8, 0x288000
	s_nop 0
	v_addc_co_u32_e32 v55, vcc, 0, v63, vcc
	v_add_co_u32_e32 v56, vcc, s8, v62
	s_mov_b32 s8, 0x2a0000
	s_nop 0
	v_addc_co_u32_e32 v57, vcc, 0, v63, vcc
	v_add_co_u32_e32 v58, vcc, s8, v62
	s_mov_b32 s8, 0x2b8000
	s_nop 0
	v_addc_co_u32_e32 v59, vcc, 0, v63, vcc
	v_add_co_u32_e32 v60, vcc, s8, v62
	s_mov_b32 s8, 0x2d0000
	s_nop 0
	v_addc_co_u32_e32 v61, vcc, 0, v63, vcc
	v_add_co_u32_e32 v64, vcc, s8, v62
	s_mov_b32 s8, 0x2e8000
	s_nop 0
	v_addc_co_u32_e32 v65, vcc, 0, v63, vcc
	v_add_co_u32_e32 v66, vcc, s8, v62
	s_mov_b32 s8, 0x300000
	s_nop 0
	v_addc_co_u32_e32 v67, vcc, 0, v63, vcc
	v_add_co_u32_e32 v68, vcc, s8, v62
	s_mov_b32 s8, 0x318000
	s_nop 0
	v_addc_co_u32_e32 v69, vcc, 0, v63, vcc
	v_add_co_u32_e32 v70, vcc, s8, v62
	s_mov_b32 s8, 0x330000
	s_nop 0
	v_addc_co_u32_e32 v71, vcc, 0, v63, vcc
	v_add_co_u32_e32 v72, vcc, s8, v62
	s_mov_b32 s8, 0x348000
	s_nop 0
	v_addc_co_u32_e32 v73, vcc, 0, v63, vcc
	v_add_co_u32_e32 v74, vcc, s8, v62
	s_mov_b32 s8, 0x360000
	s_nop 0
	v_addc_co_u32_e32 v75, vcc, 0, v63, vcc
	v_add_co_u32_e32 v76, vcc, s8, v62
	s_mov_b32 s8, 0x378000
	s_nop 0
	v_addc_co_u32_e32 v77, vcc, 0, v63, vcc
	v_add_co_u32_e32 v78, vcc, s8, v62
	s_mov_b32 s8, 0x390000
	s_nop 0
	v_addc_co_u32_e32 v79, vcc, 0, v63, vcc
	v_add_co_u32_e32 v80, vcc, s8, v62
	s_mov_b32 s8, 0x3a8000
	s_nop 0
	v_addc_co_u32_e32 v81, vcc, 0, v63, vcc
	v_add_co_u32_e32 v82, vcc, s8, v62
	s_mov_b32 s8, 0x3c0000
	s_nop 0
	v_addc_co_u32_e32 v83, vcc, 0, v63, vcc
	v_add_co_u32_e32 v84, vcc, s8, v62
	s_mov_b32 s8, 0x3d8000
	s_nop 0
	v_addc_co_u32_e32 v85, vcc, 0, v63, vcc
	v_add_co_u32_e32 v86, vcc, s8, v62
	s_mov_b32 s8, 0x3f0000
	s_nop 0
	v_addc_co_u32_e32 v87, vcc, 0, v63, vcc
	v_add_co_u32_e32 v88, vcc, s8, v62
	s_mov_b32 s8, 0x408000
	s_nop 0
	v_addc_co_u32_e32 v89, vcc, 0, v63, vcc
	v_add_co_u32_e32 v90, vcc, s8, v62
	s_mov_b32 s8, 0x420000
	s_nop 0
	v_addc_co_u32_e32 v91, vcc, 0, v63, vcc
	v_add_co_u32_e32 v92, vcc, s8, v62
	s_mov_b32 s8, 0x438000
	s_nop 0
	v_addc_co_u32_e32 v93, vcc, 0, v63, vcc
	v_add_co_u32_e32 v94, vcc, s8, v62
	s_mov_b32 s8, 0x450000
	s_nop 0
	v_addc_co_u32_e32 v95, vcc, 0, v63, vcc
	v_add_co_u32_e32 v96, vcc, s8, v62
	s_mov_b32 s8, 0x468000
	s_nop 0
	v_addc_co_u32_e32 v97, vcc, 0, v63, vcc
	v_add_co_u32_e32 v98, vcc, s8, v62
	s_mov_b32 s8, 0x480000
	s_nop 0
	v_addc_co_u32_e32 v99, vcc, 0, v63, vcc
	v_add_co_u32_e32 v100, vcc, s8, v62
	s_mov_b32 s8, 0x498000
	s_nop 0
	v_addc_co_u32_e32 v101, vcc, 0, v63, vcc
	v_add_co_u32_e32 v102, vcc, s8, v62
	s_mov_b32 s8, 0x4b0000
	s_nop 0
	v_addc_co_u32_e32 v103, vcc, 0, v63, vcc
	v_add_co_u32_e32 v104, vcc, s8, v62
	s_mov_b32 s8, 0x4c8000
	s_nop 0
; __device__ __forceinline__ void transpose_item(const float* W, int ldw, bf16_t* WT, int ldt, int koff, int k0, int nsrc, int ndst, LAS float* scr, int lane) {
;     ...
;     for (int kk = 0; kk < 64; ++kk) scr[kk * 65 + lane] = src[(size_t)kk * ldw];
	v_addc_co_u32_e32 v105, vcc, 0, v63, vcc
	v_add_co_u32_e32 v106, vcc, s8, v62
	s_mov_b32 s8, 0x4e0000
	s_nop 0
	v_addc_co_u32_e32 v107, vcc, 0, v63, vcc
	v_add_co_u32_e32 v108, vcc, s8, v62
	s_mov_b32 s8, 0x4f8000
	s_nop 0
	v_addc_co_u32_e32 v109, vcc, 0, v63, vcc
	v_add_co_u32_e32 v110, vcc, s8, v62
	s_mov_b32 s8, 0x510000
	s_nop 0
	v_addc_co_u32_e32 v111, vcc, 0, v63, vcc
	v_add_co_u32_e32 v112, vcc, s8, v62
	s_mov_b32 s8, 0x528000
	s_nop 0
	v_addc_co_u32_e32 v113, vcc, 0, v63, vcc
	v_add_co_u32_e32 v114, vcc, s8, v62
	s_mov_b32 s8, 0x540000
	s_nop 0
	v_addc_co_u32_e32 v115, vcc, 0, v63, vcc
	v_add_co_u32_e32 v116, vcc, s8, v62
	s_mov_b32 s8, 0x558000
	s_nop 0
	v_addc_co_u32_e32 v117, vcc, 0, v63, vcc
	v_add_co_u32_e32 v118, vcc, s8, v62
	s_mov_b32 s8, 0x570000
	s_nop 0
	v_addc_co_u32_e32 v119, vcc, 0, v63, vcc
	v_add_co_u32_e32 v120, vcc, s8, v62
	s_mov_b32 s8, 0x588000
	s_nop 0
	v_addc_co_u32_e32 v121, vcc, 0, v63, vcc
	v_add_co_u32_e32 v122, vcc, s8, v62
	s_mov_b32 s8, 0x5a0000
	s_nop 0
	v_addc_co_u32_e32 v123, vcc, 0, v63, vcc
	v_add_co_u32_e32 v124, vcc, s8, v62
	s_mov_b32 s8, 0x5b8000
	s_nop 0
	v_addc_co_u32_e32 v125, vcc, 0, v63, vcc
	v_add_co_u32_e32 v126, vcc, s8, v62
	s_mov_b32 s8, 0x5d0000
	s_nop 0
	v_addc_co_u32_e32 v127, vcc, 0, v63, vcc
	v_add_co_u32_e32 v128, vcc, s8, v62
	s_mov_b32 s8, 0x5e8000
	s_nop 0
	v_addc_co_u32_e32 v129, vcc, 0, v63, vcc
	v_add_co_u32_e32 v62, vcc, s8, v62
	s_mul_i32 s8, s77, 0xffffd000
	s_nop 0
	v_addc_co_u32_e32 v63, vcc, 0, v63, vcc
	global_load_dword v159, v[4:5], off nt
	s_nop 0
	global_load_dword v6, v[6:7], off nt
	s_nop 0
	global_load_dword v7, v[8:9], off nt
	global_load_dword v160, v[10:11], off nt
	s_nop 0
	global_load_dword v12, v[12:13], off nt
	s_nop 0
	global_load_dword v13, v[14:15], off nt
	s_nop 0
	global_load_dword v14, v[16:17], off nt
	global_load_dword v15, v[18:19], off nt
	s_nop 0
	global_load_dword v16, v[20:21], off nt
	global_load_dword v17, v[22:23], off nt
	global_load_dword v18, v[24:25], off nt
	global_load_dword v19, v[26:27], off nt
	s_nop 0
	global_load_dword v20, v[28:29], off nt
	global_load_dword v21, v[30:31], off nt
	global_load_dword v22, v[32:33], off nt
	global_load_dword v23, v[34:35], off nt
	global_load_dword v24, v[36:37], off nt
	global_load_dword v25, v[38:39], off nt
	global_load_dword v26, v[40:41], off nt
	global_load_dword v27, v[42:43], off nt
	global_load_dword v28, v[44:45], off nt
	global_load_dword v29, v[46:47], off nt
	global_load_dword v30, v[48:49], off nt
	global_load_dword v31, v[50:51], off nt
	global_load_dword v32, v[52:53], off nt
	global_load_dword v33, v[54:55], off nt
	global_load_dword v34, v[56:57], off nt
	global_load_dword v35, v[58:59], off nt
	global_load_dword v36, v[60:61], off nt
	global_load_dword v37, v[64:65], off nt
	global_load_dword v38, v[66:67], off nt
	global_load_dword v39, v[68:69], off nt
	global_load_dword v40, v[70:71], off nt
	global_load_dword v41, v[72:73], off nt
	global_load_dword v42, v[74:75], off nt
	global_load_dword v43, v[76:77], off nt
	global_load_dword v44, v[78:79], off nt
	global_load_dword v45, v[80:81], off nt
	global_load_dword v46, v[82:83], off nt
	global_load_dword v47, v[84:85], off nt
	global_load_dword v48, v[86:87], off nt
	global_load_dword v49, v[88:89], off nt
	global_load_dword v50, v[90:91], off nt
	global_load_dword v51, v[92:93], off nt
	global_load_dword v52, v[94:95], off nt
	global_load_dword v53, v[96:97], off nt
	global_load_dword v54, v[98:99], off nt
	global_load_dword v55, v[100:101], off nt
	global_load_dword v56, v[102:103], off nt
	global_load_dword v57, v[104:105], off nt
	global_load_dword v58, v[106:107], off nt
	global_load_dword v59, v[108:109], off nt
	global_load_dword v60, v[110:111], off nt
	global_load_dword v61, v[112:113], off nt
	global_load_dword v64, v[114:115], off nt
	global_load_dword v65, v[116:117], off nt
	global_load_dword v66, v[118:119], off nt
	global_load_dword v67, v[120:121], off nt
	global_load_dword v68, v[122:123], off nt
	global_load_dword v69, v[124:125], off nt
	global_load_dword v70, v[126:127], off nt
	global_load_dword v71, v[128:129], off nt
	s_nop 0
	global_load_dword v62, v[62:63], off nt
	s_add_i32 s8, s23, s8
	s_andn2_b32 s8, s8, 63
	s_waitcnt vmcnt(62)
	ds_write2_b32 v1, v158, v159 offset1:65
	s_waitcnt vmcnt(60)
	ds_write2_b32 v1, v6, v7 offset0:130 offset1:195
	s_waitcnt vmcnt(58)
	ds_write2_b32 v142, v160, v12 offset0:4 offset1:69
	s_waitcnt vmcnt(56)
	ds_write2_b32 v142, v13, v14 offset0:134 offset1:199
	s_waitcnt vmcnt(54)
	ds_write2_b32 v143, v15, v16 offset0:8 offset1:73
	s_waitcnt vmcnt(52)
	ds_write2_b32 v143, v17, v18 offset0:138 offset1:203
	s_waitcnt vmcnt(50)
	ds_write2_b32 v144, v19, v20 offset0:12 offset1:77
	s_waitcnt vmcnt(48)
	ds_write2_b32 v144, v21, v22 offset0:142 offset1:207
	s_waitcnt vmcnt(46)
	ds_write2_b32 v145, v23, v24 offset0:16 offset1:81
	s_waitcnt vmcnt(44)
	ds_write2_b32 v145, v25, v26 offset0:146 offset1:211
	s_waitcnt vmcnt(42)
	ds_write2_b32 v146, v27, v28 offset0:20 offset1:85
	s_waitcnt vmcnt(40)
	ds_write2_b32 v146, v29, v30 offset0:150 offset1:215
	s_waitcnt vmcnt(38)
	ds_write2_b32 v147, v31, v32 offset0:24 offset1:89
	s_waitcnt vmcnt(36)
	ds_write2_b32 v147, v33, v34 offset0:154 offset1:219
	s_waitcnt vmcnt(34)
	ds_write2_b32 v148, v35, v36 offset0:28 offset1:93
	s_waitcnt vmcnt(32)
	ds_write2_b32 v148, v37, v38 offset0:158 offset1:223
	s_waitcnt vmcnt(30)
	ds_write2_b32 v149, v39, v40 offset0:32 offset1:97
	s_waitcnt vmcnt(28)
	ds_write2_b32 v149, v41, v42 offset0:162 offset1:227
	s_waitcnt vmcnt(26)
	ds_write2_b32 v150, v43, v44 offset0:36 offset1:101
	s_waitcnt vmcnt(24)
; #define LAS __attribute__((address_space(3)))
; __device__ __forceinline__ unsigned pk2(float lo, float hi) { return __builtin_bit_cast(unsigned, __builtin_convertvector((f32x2){lo, hi}, bf16x2_t)); }
; #define LDS_WAIT() asm volatile("s_waitcnt lgkmcnt(0)" ::: "memory")
; __device__ __forceinline__ void transpose_item(const float* W, int ldw, bf16_t* WT, int ldt, int koff, int k0, int nsrc, int ndst, LAS float* scr, int lane) {
;     ...
;     LDS_WAIT(); asm volatile("" ::: "memory");
;     const int c = lane & 7;
; #pragma unroll
;     for (int j = 0; j < 8; ++j) { const int n = (lane >> 3) + 8 * j; const LAS float* s = scr + (8 * c) * 65 + n;
;         u32x4 o; o.x = pk2(s[0 * 65], s[1 * 65]); o.y = pk2(s[2 * 65], s[3 * 65]); o.z = pk2(s[4 * 65], s[5 * 65]); o.w = pk2(s[6 * 65], s[7 * 65]);
;         *(u32x4*)((char*)WT + tiled_off_b(ndst + n, koff + k0 + 8 * c)) = o; }
	ds_write2_b32 v150, v45, v46 offset0:166 offset1:231
	s_waitcnt vmcnt(22)
	ds_write2_b32 v151, v47, v48 offset0:40 offset1:105
	s_waitcnt vmcnt(20)
	ds_write2_b32 v151, v49, v50 offset0:170 offset1:235
	s_waitcnt vmcnt(18)
	ds_write2_b32 v152, v51, v52 offset0:44 offset1:109
	s_waitcnt vmcnt(16)
	ds_write2_b32 v152, v53, v54 offset0:174 offset1:239
	s_waitcnt vmcnt(14)
	ds_write2_b32 v153, v55, v56 offset0:48 offset1:113
	s_waitcnt vmcnt(12)
	ds_write2_b32 v153, v57, v58 offset0:178 offset1:243
	s_waitcnt vmcnt(10)
	ds_write2_b32 v154, v59, v60 offset0:52 offset1:117
	s_waitcnt vmcnt(8)
	ds_write2_b32 v154, v61, v64 offset0:182 offset1:247
	s_waitcnt vmcnt(6)
	ds_write2_b32 v155, v65, v66 offset0:56 offset1:121
	s_waitcnt vmcnt(4)
	ds_write2_b32 v155, v67, v68 offset0:186 offset1:251
	s_waitcnt vmcnt(2)
	ds_write2_b32 v156, v69, v70 offset0:60 offset1:125
	s_waitcnt vmcnt(0)
	ds_write2_b32 v156, v71, v62 offset0:190 offset1:255
	s_add_i32 s8, s8, s77
	v_add_u32_e32 v4, s0, v135
	s_waitcnt lgkmcnt(0)
	s_ashr_i32 s9, s8, 31
	v_lshrrev_b32_e32 v4, 3, v4
	s_lshl_b64 s[8:9], s[8:9], 14
	v_and_or_b32 v4, v4, 10, v131
	ds_read2_b32 v[12:13], v134 offset0:65 offset1:73
	ds_read2_b32 v[14:15], v134 offset1:8
	ds_read2_b32 v[16:17], v134 offset0:130 offset1:138
	ds_read2_b32 v[18:19], v134 offset0:195 offset1:203
	ds_read2_b32 v[20:21], v157 offset0:4 offset1:12
	ds_read2_b32 v[22:23], v157 offset0:69 offset1:77
	ds_read2_b32 v[24:25], v157 offset0:134 offset1:142
	ds_read2_b32 v[26:27], v157 offset0:199 offset1:207
	s_add_u32 s8, s14, s8
	v_lshlrev_b32_e32 v63, 10, v4
	s_addc_u32 s9, s15, s9
	v_or_b32_e32 v8, v63, v136
	v_mov_b32_e32 v9, v3
	v_lshl_add_u64 v[4:5], s[8:9], 0, v[8:9]
	v_add_co_u32_e32 v10, vcc, s10, v4
	s_mul_i32 s77, s77, 0xffe80000
	v_add_u32_e32 v72, s0, v140
	v_addc_co_u32_e32 v11, vcc, 0, v5, vcc
	v_add_u32_e32 v9, s77, v141
	s_waitcnt lgkmcnt(6)
	v_cvt_pk_bf16_f32 v4, v14, v12
	s_waitcnt lgkmcnt(4)
	v_cvt_pk_bf16_f32 v5, v16, v18
	s_waitcnt lgkmcnt(2)
	v_cvt_pk_bf16_f32 v6, v20, v22
	s_waitcnt lgkmcnt(0)
	v_cvt_pk_bf16_f32 v7, v24, v26
	v_lshrrev_b32_e32 v12, 3, v72
	global_store_dwordx4 v8, v[4:7], s[8:9] nt
	v_and_or_b32 v12, v12, 10, v131
	v_lshlrev_b32_e32 v12, 10, v12
	v_cvt_pk_bf16_f32 v4, v15, v13
	v_and_or_b32 v13, v9, s20, v138
	v_lshrrev_b32_e32 v9, 4, v9
	v_and_b32_e32 v9, 32, v9
	v_cvt_pk_bf16_f32 v5, v17, v19
	v_cvt_pk_bf16_f32 v6, v21, v23
	v_cvt_pk_bf16_f32 v7, v25, v27
	v_bitop3_b32 v9, v13, v12, v9 bitop3:0xde
	ds_read2_b32 v[12:13], v134 offset0:16 offset1:24
	ds_read2_b32 v[14:15], v134 offset0:81 offset1:89
	ds_read2_b32 v[16:17], v134 offset0:146 offset1:154
	ds_read2_b32 v[18:19], v134 offset0:211 offset1:219
	ds_read2_b32 v[20:21], v157 offset0:20 offset1:28
	ds_read2_b32 v[22:23], v157 offset0:85 offset1:93
	ds_read2_b32 v[24:25], v157 offset0:150 offset1:158
	ds_read2_b32 v[26:27], v157 offset0:215 offset1:223
	global_store_dwordx4 v9, v[4:7], s[8:9] nt
	v_xor_b32_e32 v8, 32, v8
	v_mov_b32_e32 v9, v3
	v_add_u32_e32 v28, s0, v133
	s_waitcnt lgkmcnt(6)
	v_cvt_pk_bf16_f32 v4, v12, v14
	s_waitcnt lgkmcnt(4)
	v_cvt_pk_bf16_f32 v5, v16, v18
	s_waitcnt lgkmcnt(2)
	v_cvt_pk_bf16_f32 v6, v20, v22
	s_waitcnt lgkmcnt(0)
	v_cvt_pk_bf16_f32 v7, v24, v26
	v_lshl_add_u64 v[8:9], s[8:9], 0, v[8:9]
	global_store_dwordx4 v[8:9], v[4:7], off offset:512 nt
	v_lshrrev_b32_e32 v8, 3, v28
	v_and_or_b32 v8, v8, 10, v131
	v_cvt_pk_bf16_f32 v4, v13, v15
	v_cvt_pk_bf16_f32 v5, v17, v19
	v_cvt_pk_bf16_f32 v6, v21, v23
	v_cvt_pk_bf16_f32 v7, v25, v27
	ds_read2_b32 v[12:13], v134 offset0:32 offset1:40
	ds_read2_b32 v[14:15], v134 offset0:97 offset1:105
	ds_read2_b32 v[16:17], v134 offset0:162 offset1:170
	ds_read2_b32 v[18:19], v134 offset0:227 offset1:235
	ds_read2_b32 v[20:21], v157 offset0:36 offset1:44
	ds_read2_b32 v[22:23], v157 offset0:101 offset1:109
	ds_read2_b32 v[24:25], v157 offset0:166 offset1:174
	ds_read2_b32 v[26:27], v157 offset0:231 offset1:239
	v_lshlrev_b32_e32 v28, 10, v8
	v_or_b32_e32 v8, v28, v136
	v_xor_b32_e32 v8, 32, v8
	v_mov_b32_e32 v9, v3
	v_lshl_add_u64 v[8:9], s[8:9], 0, v[8:9]
	global_store_dwordx4 v[8:9], v[4:7], off offset:768 nt
	s_movk_i32 s0, 0x1220
	s_waitcnt lgkmcnt(6)
	v_cvt_pk_bf16_f32 v4, v12, v14
	s_waitcnt lgkmcnt(4)
	v_cvt_pk_bf16_f32 v5, v16, v18
	s_waitcnt lgkmcnt(2)
	v_cvt_pk_bf16_f32 v6, v20, v22
	s_waitcnt lgkmcnt(0)
	v_cvt_pk_bf16_f32 v7, v24, v26
	global_store_dwordx4 v[10:11], v[4:7], off nt
	v_or_b32_e32 v24, v63, v139
	s_nop 0
	v_cvt_pk_bf16_f32 v4, v13, v15
	v_cvt_pk_bf16_f32 v5, v17, v19
	v_cvt_pk_bf16_f32 v6, v21, v23
	ds_read2_b32 v[8:9], v134 offset0:48 offset1:56
	ds_read2_b32 v[10:11], v134 offset0:113 offset1:121
	ds_read2_b32 v[12:13], v134 offset0:178 offset1:186
	ds_read2_b32 v[14:15], v134 offset0:243 offset1:251
	ds_read2_b32 v[16:17], v157 offset0:52 offset1:60
	ds_read2_b32 v[18:19], v157 offset0:117 offset1:125
	ds_read2_b32 v[20:21], v157 offset0:182 offset1:190
	ds_read2_b32 v[22:23], v157 offset0:247 offset1:255
	v_cvt_pk_bf16_f32 v7, v25, v27
	global_store_dwordx4 v24, v[4:7], s[8:9] nt
	s_waitcnt lgkmcnt(6)
	s_nop 0
	v_cvt_pk_bf16_f32 v4, v8, v10
	s_waitcnt lgkmcnt(4)
	v_cvt_pk_bf16_f32 v5, v12, v14
	s_waitcnt lgkmcnt(2)
	v_cvt_pk_bf16_f32 v6, v16, v18
	s_waitcnt lgkmcnt(0)
	v_cvt_pk_bf16_f32 v7, v20, v22
	v_bitop3_b32 v8, v63, s0, v136 bitop3:0x36
	s_movk_i32 s0, 0x1320
	global_store_dwordx4 v8, v[4:7], s[8:9] nt
	v_bitop3_b32 v8, v28, s0, v136 bitop3:0x36
	s_nop 0
	v_cvt_pk_bf16_f32 v4, v9, v11
	v_cvt_pk_bf16_f32 v5, v13, v15
	v_cvt_pk_bf16_f32 v6, v17, v19
	v_cvt_pk_bf16_f32 v7, v21, v23
	global_store_dwordx4 v8, v[4:7], s[8:9] nt
	s_waitcnt lgkmcnt(0)

; __device__ __forceinline__ void transpose_item(const float* W, int ldw, bf16_t* WT, int ldt, int koff, int k0, int nsrc, int ndst, LAS float* scr, int lane) {
;     const float* src = W + (size_t)k0 * ldw + nsrc + lane;
; #pragma unroll 32
;     for (int kk = 0; kk < 64; ++kk) scr[kk * 65 + lane] = src[(size_t)kk * ldw];
; __device__ __forceinline__ void phase0(const Args& a, LAS unsigned char* lds, int bid, int G) {
;     ...
;     for (int it = gw; it < NITEMS; it += NGW) {
;         int r = it;
;         if (r < I_IN) { const int kb = r / 384, nb = r - kb * 384; transpose_item(a.w_in, PC, WinT, LDP, 0, 64 * kb, proj_src_col(64 * nb), 64 * nb, scr, lane); continue; } r -= I_IN;
;         if (r < I_B) { const int kb = r >> 6, nb = r & 63; transpose_item(a.w_branch, DM, WbT, LDP, 0, 64 * kb, 64 * nb, 64 * nb, scr, lane); continue; } r -= I_B;
;         if (r < I_B) { const int kb = r >> 6, nb = r & 63; transpose_item(a.w_branch + (size_t)BW * DM, DM, WbT, LDP, BW, 64 * kb, 64 * nb, 64 * nb, scr, lane); continue; } r -= I_B;
;         { const int kb = r >> 6, nb = r & 63; transpose_item(a.w_out, DM, WoT, LDP, 0, 64 * kb, 64 * nb, 64 * nb, scr, lane); }
.LBB0_22:
	s_cmpk_gt_i32 s12, 0x5fff
	s_mov_b64 s[8:9], -1
	s_cbranch_scc0 .LBB0_32
	s_cmpk_gt_u32 s12, 0x67ff
	s_cbranch_scc0 .LBB0_29
	s_and_b32 s10, s25, 0xfc0
	s_cmpk_gt_u32 s12, 0x6fff
	s_cbranch_scc0 .LBB0_26
	s_and_b32 s0, s12, 0x7fffffc0
	s_addk_i32 s0, 0x9000
	v_readlane_b32 s80, v252, 0
	s_lshl_b64 s[8:9], s[0:1], 14
	v_readlane_b32 s84, v252, 4
	v_readlane_b32 s85, v252, 5
	s_add_u32 s8, s84, s8
	s_addc_u32 s9, s85, s9
	s_lshl_b32 s11, s10, 2
	s_add_u32 s8, s8, s11
	s_addc_u32 s9, s9, 0
	v_lshl_add_u64 v[4:5], s[8:9], 0, v[2:3]
	global_load_dword v6, v2, s[8:9] nt
	s_movk_i32 s8, 0x4000
	v_add_co_u32_e32 v8, vcc, s8, v4
	s_mov_b32 s8, 0x8000
	s_nop 0
	v_addc_co_u32_e32 v9, vcc, 0, v5, vcc
	v_add_co_u32_e32 v10, vcc, s8, v4
	s_mov_b32 s8, 0xc000
	s_nop 0
	v_addc_co_u32_e32 v11, vcc, 0, v5, vcc
	v_add_co_u32_e32 v12, vcc, s8, v4
	s_mov_b32 s8, 0x10000
	s_nop 0
	v_addc_co_u32_e32 v13, vcc, 0, v5, vcc
	v_add_co_u32_e32 v14, vcc, s8, v4
	s_mov_b32 s8, 0x14000
	s_nop 0
	v_addc_co_u32_e32 v15, vcc, 0, v5, vcc
	v_add_co_u32_e32 v16, vcc, s8, v4
	s_mov_b32 s8, 0x1c000
	s_nop 0
	v_addc_co_u32_e32 v17, vcc, 0, v5, vcc
	v_add_co_u32_e32 v18, vcc, s69, v4
	s_lshr_b32 s0, s0, 6
	s_nop 0
	v_addc_co_u32_e32 v19, vcc, 0, v5, vcc
	v_add_co_u32_e32 v20, vcc, s8, v4
	s_mov_b32 s8, 0x20000
	s_nop 0
	v_addc_co_u32_e32 v21, vcc, 0, v5, vcc
	v_add_co_u32_e32 v22, vcc, s8, v4
	s_mov_b32 s8, 0x24000
	s_nop 0
	v_addc_co_u32_e32 v23, vcc, 0, v5, vcc
	global_load_dword v7, v[8:9], off nt
	s_nop 0
	global_load_dword v8, v[10:11], off nt
	global_load_dword v9, v[12:13], off nt
	s_nop 0
	global_load_dword v10, v[14:15], off nt
	global_load_dword v11, v[16:17], off nt
	global_load_dword v12, v[18:19], off nt
	global_load_dword v13, v[20:21], off nt
	s_nop 0
	global_load_dword v14, v[22:23], off nt
	v_add_co_u32_e32 v16, vcc, s8, v4
	s_mov_b32 s8, 0x28000
	s_nop 0
	v_addc_co_u32_e32 v17, vcc, 0, v5, vcc
	v_add_co_u32_e32 v18, vcc, s8, v4
	s_mov_b32 s8, 0x2c000
	s_nop 0
	v_addc_co_u32_e32 v19, vcc, 0, v5, vcc
	v_add_co_u32_e32 v20, vcc, s8, v4
	s_mov_b32 s8, 0x34000
	s_nop 0
	v_addc_co_u32_e32 v21, vcc, 0, v5, vcc
	v_add_co_u32_e32 v22, vcc, s75, v4
	v_readlane_b32 s81, v252, 1
	s_nop 0
	v_addc_co_u32_e32 v23, vcc, 0, v5, vcc
	v_add_co_u32_e32 v24, vcc, s8, v4
	s_mov_b32 s8, 0x38000
	s_nop 0
	v_addc_co_u32_e32 v25, vcc, 0, v5, vcc
	v_add_co_u32_e32 v26, vcc, s8, v4
	s_mov_b32 s8, 0x3c000
	s_nop 0
	v_addc_co_u32_e32 v27, vcc, 0, v5, vcc
	v_add_co_u32_e32 v28, vcc, s8, v4
	s_mov_b32 s8, 0x40000
	s_nop 0
	v_addc_co_u32_e32 v29, vcc, 0, v5, vcc
	v_add_co_u32_e32 v30, vcc, s8, v4
	s_mov_b32 s8, 0x44000
	s_nop 0
	v_addc_co_u32_e32 v31, vcc, 0, v5, vcc
	global_load_dword v15, v[16:17], off nt
	s_nop 0
	global_load_dword v16, v[18:19], off nt
	global_load_dword v17, v[20:21], off nt
	s_nop 0
	global_load_dword v18, v[22:23], off nt
	global_load_dword v19, v[24:25], off nt
	global_load_dword v20, v[26:27], off nt
	global_load_dword v21, v[28:29], off nt
	s_nop 0
	global_load_dword v22, v[30:31], off nt
	v_add_co_u32_e32 v24, vcc, s8, v4
	s_mov_b32 s8, 0x4c000
	s_nop 0
	v_addc_co_u32_e32 v25, vcc, 0, v5, vcc
	v_add_co_u32_e32 v26, vcc, s88, v4
	v_readlane_b32 s82, v252, 2
	s_nop 0
	v_addc_co_u32_e32 v27, vcc, 0, v5, vcc
	v_add_co_u32_e32 v28, vcc, s8, v4
	s_mov_b32 s8, 0x50000
	s_nop 0
	v_addc_co_u32_e32 v29, vcc, 0, v5, vcc
	v_add_co_u32_e32 v30, vcc, s8, v4
	s_mov_b32 s8, 0x54000
	s_nop 0
	v_addc_co_u32_e32 v31, vcc, 0, v5, vcc
	v_add_co_u32_e32 v32, vcc, s8, v4
	s_mov_b32 s8, 0x58000
	s_nop 0
	v_addc_co_u32_e32 v33, vcc, 0, v5, vcc
	v_add_co_u32_e32 v34, vcc, s8, v4
	s_mov_b32 s8, 0x5c000
	s_nop 0
	v_addc_co_u32_e32 v35, vcc, 0, v5, vcc
	v_add_co_u32_e32 v36, vcc, s8, v4
	s_mov_b32 s8, 0x64000
	s_nop 0
	v_addc_co_u32_e32 v37, vcc, 0, v5, vcc
	v_add_co_u32_e32 v38, vcc, s89, v4
	v_readlane_b32 s83, v252, 3
	s_nop 0
	v_addc_co_u32_e32 v39, vcc, 0, v5, vcc
	global_load_dword v23, v[24:25], off nt
	global_load_dword v40, v[26:27], off nt
	global_load_dword v41, v[28:29], off nt
	global_load_dword v42, v[30:31], off nt
	global_load_dword v43, v[32:33], off nt
	global_load_dword v44, v[34:35], off nt
	global_load_dword v45, v[36:37], off nt
	global_load_dword v46, v[38:39], off nt
	v_add_co_u32_e32 v24, vcc, s8, v4
	s_mov_b32 s8, 0x68000
	s_nop 0
	v_addc_co_u32_e32 v25, vcc, 0, v5, vcc
	v_add_co_u32_e32 v26, vcc, s8, v4
	s_and_b32 s8, s23, 0x7c0
	s_nop 0
	v_addc_co_u32_e32 v27, vcc, 0, v5, vcc
	v_add_co_u32_e32 v28, vcc, s90, v4
	s_add_i32 s0, s0, s8
	s_nop 0
	v_addc_co_u32_e32 v29, vcc, 0, v5, vcc
	v_add_co_u32_e32 v30, vcc, s91, v4
	s_lshl_b64 s[8:9], s[0:1], 14
	s_nop 0
	v_addc_co_u32_e32 v31, vcc, 0, v5, vcc
	v_add_co_u32_e32 v32, vcc, s92, v4
	v_readlane_b32 s0, v252, 18
	s_nop 0
	v_addc_co_u32_e32 v33, vcc, 0, v5, vcc
	v_add_co_u32_e32 v34, vcc, s93, v4
	s_add_u32 s8, s0, s8
	s_nop 0
	v_addc_co_u32_e32 v35, vcc, 0, v5, vcc
	v_add_co_u32_e32 v36, vcc, s94, v4
	v_readlane_b32 s0, v252, 19
	s_nop 0
	v_addc_co_u32_e32 v37, vcc, 0, v5, vcc
	v_add_co_u32_e32 v38, vcc, s95, v4
	s_addc_u32 s9, s0, s9
	s_nop 0
	v_addc_co_u32_e32 v39, vcc, 0, v5, vcc
	global_load_dword v47, v[24:25], off nt
	global_load_dword v48, v[26:27], off nt
	global_load_dword v49, v[28:29], off nt
	global_load_dword v50, v[30:31], off nt
	global_load_dword v51, v[32:33], off nt
	global_load_dword v52, v[34:35], off nt
	global_load_dword v53, v[36:37], off nt
	global_load_dword v54, v[38:39], off nt
	v_add_co_u32_e32 v24, vcc, s96, v4
	v_readlane_b32 s86, v252, 6
	s_nop 0
	v_addc_co_u32_e32 v25, vcc, 0, v5, vcc
	v_add_co_u32_e32 v26, vcc, s97, v4
	v_readlane_b32 s87, v252, 7
	s_nop 0
; #define LDS_WAIT() asm volatile("s_waitcnt lgkmcnt(0)" ::: "memory")
; __device__ __forceinline__ void transpose_item(const float* W, int ldw, bf16_t* WT, int ldt, int koff, int k0, int nsrc, int ndst, LAS float* scr, int lane) {
;     const float* src = W + (size_t)k0 * ldw + nsrc + lane;
; #pragma unroll 32
;     for (int kk = 0; kk < 64; ++kk) scr[kk * 65 + lane] = src[(size_t)kk * ldw];
;     LDS_WAIT(); asm volatile("" ::: "memory");
	v_addc_co_u32_e32 v27, vcc, 0, v5, vcc
	v_add_co_u32_e32 v28, vcc, s26, v4
	s_nop 1
	v_addc_co_u32_e32 v29, vcc, 0, v5, vcc
	v_add_co_u32_e32 v30, vcc, s27, v4
	s_nop 1
	v_addc_co_u32_e32 v31, vcc, 0, v5, vcc
	v_add_co_u32_e32 v32, vcc, s60, v4
	s_nop 1
	v_addc_co_u32_e32 v33, vcc, 0, v5, vcc
	v_add_co_u32_e32 v34, vcc, s61, v4
	s_nop 1
	v_addc_co_u32_e32 v35, vcc, 0, v5, vcc
	v_add_co_u32_e32 v36, vcc, s52, v4
	s_nop 1
	v_addc_co_u32_e32 v37, vcc, 0, v5, vcc
	v_add_co_u32_e32 v38, vcc, s53, v4
	s_nop 1
	v_addc_co_u32_e32 v39, vcc, 0, v5, vcc
	global_load_dword v55, v[24:25], off nt
	global_load_dword v56, v[26:27], off nt
	global_load_dword v57, v[28:29], off nt
	global_load_dword v58, v[30:31], off nt
	global_load_dword v59, v[32:33], off nt
	global_load_dword v60, v[34:35], off nt
	global_load_dword v61, v[36:37], off nt
	global_load_dword v62, v[38:39], off nt
	v_add_co_u32_e32 v24, vcc, s54, v4
	s_nop 1
	v_addc_co_u32_e32 v25, vcc, 0, v5, vcc
	v_add_co_u32_e32 v26, vcc, s55, v4
	s_nop 1
	v_addc_co_u32_e32 v27, vcc, 0, v5, vcc
	v_add_co_u32_e32 v28, vcc, s56, v4
	s_nop 1
	v_addc_co_u32_e32 v29, vcc, 0, v5, vcc
	v_add_co_u32_e32 v30, vcc, s57, v4
	s_nop 1
	v_addc_co_u32_e32 v31, vcc, 0, v5, vcc
	v_add_co_u32_e32 v32, vcc, s58, v4
	s_nop 1
	v_addc_co_u32_e32 v33, vcc, 0, v5, vcc
	v_add_co_u32_e32 v34, vcc, s59, v4
	s_nop 1
	v_addc_co_u32_e32 v35, vcc, 0, v5, vcc
	v_add_co_u32_e32 v36, vcc, s18, v4
	s_nop 1
	v_addc_co_u32_e32 v37, vcc, 0, v5, vcc
	v_add_co_u32_e32 v38, vcc, s19, v4
	s_nop 1
	v_addc_co_u32_e32 v39, vcc, 0, v5, vcc
	global_load_dword v63, v[24:25], off nt
	global_load_dword v64, v[26:27], off nt
	global_load_dword v65, v[28:29], off nt
	global_load_dword v66, v[30:31], off nt
	global_load_dword v67, v[32:33], off nt
	global_load_dword v68, v[34:35], off nt
	global_load_dword v69, v[36:37], off nt
	global_load_dword v70, v[38:39], off nt
	v_add_co_u32_e32 v24, vcc, s21, v4
	s_nop 1
	v_addc_co_u32_e32 v25, vcc, 0, v5, vcc
	v_add_co_u32_e32 v26, vcc, s22, v4
	s_nop 1
	v_addc_co_u32_e32 v27, vcc, 0, v5, vcc
	v_add_co_u32_e32 v28, vcc, s3, v4
	s_nop 1
	v_addc_co_u32_e32 v29, vcc, 0, v5, vcc
	v_add_co_u32_e32 v30, vcc, s13, v4
	s_nop 1
	v_addc_co_u32_e32 v31, vcc, 0, v5, vcc
	v_add_co_u32_e32 v32, vcc, s34, v4
	s_nop 1
	v_addc_co_u32_e32 v33, vcc, 0, v5, vcc
	v_add_co_u32_e32 v34, vcc, s35, v4
	s_nop 1
	v_addc_co_u32_e32 v35, vcc, 0, v5, vcc
	v_add_co_u32_e32 v36, vcc, s64, v4
	s_nop 1
	v_addc_co_u32_e32 v37, vcc, 0, v5, vcc
	v_add_co_u32_e32 v38, vcc, s65, v4
	s_nop 1
	v_addc_co_u32_e32 v39, vcc, 0, v5, vcc
	global_load_dword v71, v[24:25], off nt
	global_load_dword v72, v[26:27], off nt
	global_load_dword v73, v[28:29], off nt
	global_load_dword v74, v[30:31], off nt
	global_load_dword v75, v[32:33], off nt
	global_load_dword v76, v[34:35], off nt
	s_nop 0
	global_load_dword v36, v[36:37], off nt
	s_nop 0
	global_load_dword v37, v[38:39], off nt
	v_add_co_u32_e32 v24, vcc, s66, v4
	s_nop 1
	v_addc_co_u32_e32 v25, vcc, 0, v5, vcc
	v_add_co_u32_e32 v26, vcc, s67, v4
	s_nop 1
	v_addc_co_u32_e32 v27, vcc, 0, v5, vcc
	v_add_co_u32_e32 v28, vcc, s68, v4
	s_nop 1
	v_addc_co_u32_e32 v29, vcc, 0, v5, vcc
	v_add_co_u32_e32 v30, vcc, s70, v4
	s_nop 1
	v_addc_co_u32_e32 v31, vcc, 0, v5, vcc
	v_add_co_u32_e32 v32, vcc, s71, v4
	s_nop 1
	v_addc_co_u32_e32 v33, vcc, 0, v5, vcc
	v_add_co_u32_e32 v34, vcc, s72, v4
	s_nop 1
	v_addc_co_u32_e32 v35, vcc, 0, v5, vcc
	v_add_co_u32_e32 v4, vcc, s73, v4
	s_nop 1
	v_addc_co_u32_e32 v5, vcc, 0, v5, vcc
	global_load_dword v24, v[24:25], off nt
	s_nop 0
	global_load_dword v25, v[26:27], off nt
	s_nop 0
	global_load_dword v26, v[28:29], off nt
	global_load_dword v27, v[30:31], off nt
	s_nop 0
	global_load_dword v28, v[32:33], off nt
	global_load_dword v29, v[34:35], off nt
	s_nop 0
	global_load_dword v4, v[4:5], off nt
	s_waitcnt vmcnt(62)
	ds_write2_b32 v1, v6, v7 offset1:65
	s_waitcnt vmcnt(60)
	ds_write2_b32 v1, v8, v9 offset0:130 offset1:195
	s_waitcnt vmcnt(58)
	ds_write2_b32 v142, v10, v11 offset0:4 offset1:69
	s_waitcnt vmcnt(56)
	ds_write2_b32 v142, v12, v13 offset0:134 offset1:199
	s_waitcnt vmcnt(54)
	ds_write2_b32 v143, v14, v15 offset0:8 offset1:73
	s_waitcnt vmcnt(52)
	ds_write2_b32 v143, v16, v17 offset0:138 offset1:203
	s_waitcnt vmcnt(50)
	ds_write2_b32 v144, v18, v19 offset0:12 offset1:77
	s_waitcnt vmcnt(48)
	ds_write2_b32 v144, v20, v21 offset0:142 offset1:207
	s_waitcnt vmcnt(46)
	ds_write2_b32 v145, v22, v23 offset0:16 offset1:81
	s_waitcnt vmcnt(44)
	ds_write2_b32 v145, v40, v41 offset0:146 offset1:211
	s_waitcnt vmcnt(42)
	ds_write2_b32 v146, v42, v43 offset0:20 offset1:85
	s_waitcnt vmcnt(40)
	ds_write2_b32 v146, v44, v45 offset0:150 offset1:215
	s_waitcnt vmcnt(38)
	ds_write2_b32 v147, v46, v47 offset0:24 offset1:89
	s_waitcnt vmcnt(36)
	ds_write2_b32 v147, v48, v49 offset0:154 offset1:219
	s_waitcnt vmcnt(34)
	ds_write2_b32 v148, v50, v51 offset0:28 offset1:93
	s_waitcnt vmcnt(32)
	ds_write2_b32 v148, v52, v53 offset0:158 offset1:223
	s_waitcnt vmcnt(30)
	ds_write2_b32 v149, v54, v55 offset0:32 offset1:97
	s_waitcnt vmcnt(28)
	ds_write2_b32 v149, v56, v57 offset0:162 offset1:227
	s_waitcnt vmcnt(26)
	ds_write2_b32 v150, v58, v59 offset0:36 offset1:101
	s_waitcnt vmcnt(24)
	ds_write2_b32 v150, v60, v61 offset0:166 offset1:231
	s_waitcnt vmcnt(22)
	ds_write2_b32 v151, v62, v63 offset0:40 offset1:105
	s_waitcnt vmcnt(20)
	ds_write2_b32 v151, v64, v65 offset0:170 offset1:235
	s_waitcnt vmcnt(18)
	ds_write2_b32 v152, v66, v67 offset0:44 offset1:109
	s_waitcnt vmcnt(16)
	ds_write2_b32 v152, v68, v69 offset0:174 offset1:239
	s_waitcnt vmcnt(14)
; #define LAS __attribute__((address_space(3)))
; __device__ __forceinline__ unsigned pk2(float lo, float hi) { return __builtin_bit_cast(unsigned, __builtin_convertvector((f32x2){lo, hi}, bf16x2_t)); }
; #define LDS_WAIT() asm volatile("s_waitcnt lgkmcnt(0)" ::: "memory")
; __device__ __forceinline__ void transpose_item(const float* W, int ldw, bf16_t* WT, int ldt, int koff, int k0, int nsrc, int ndst, LAS float* scr, int lane) {
;     ...
;     LDS_WAIT(); asm volatile("" ::: "memory");
;     const int c = lane & 7;
; #pragma unroll
;     for (int j = 0; j < 8; ++j) { const int n = (lane >> 3) + 8 * j; const LAS float* s = scr + (8 * c) * 65 + n;
;         u32x4 o; o.x = pk2(s[0 * 65], s[1 * 65]); o.y = pk2(s[2 * 65], s[3 * 65]); o.z = pk2(s[4 * 65], s[5 * 65]); o.w = pk2(s[6 * 65], s[7 * 65]);
;         *(u32x4*)((char*)WT + tiled_off_b(ndst + n, koff + k0 + 8 * c)) = o; }
;     LDS_WAIT(); asm volatile("" ::: "memory");
	ds_write2_b32 v153, v70, v71 offset0:48 offset1:113
	s_waitcnt vmcnt(12)
	ds_write2_b32 v153, v72, v73 offset0:178 offset1:243
	s_waitcnt vmcnt(10)
	ds_write2_b32 v154, v74, v75 offset0:52 offset1:117
	s_waitcnt vmcnt(8)
	ds_write2_b32 v154, v76, v36 offset0:182 offset1:247
	s_waitcnt vmcnt(6)
	ds_write2_b32 v155, v37, v24 offset0:56 offset1:121
	s_waitcnt vmcnt(4)
	ds_write2_b32 v155, v25, v26 offset0:186 offset1:251
	s_waitcnt vmcnt(2)
	ds_write2_b32 v156, v27, v28 offset0:60 offset1:125
	s_waitcnt vmcnt(0)
	ds_write2_b32 v156, v29, v4 offset0:190 offset1:255
	s_waitcnt lgkmcnt(0)
	v_add_u32_e32 v26, s25, v130
	ds_read2_b32 v[8:9], v134 offset0:65 offset1:73
	ds_read2_b32 v[10:11], v134 offset1:8
	ds_read2_b32 v[12:13], v134 offset0:130 offset1:138
	ds_read2_b32 v[14:15], v134 offset0:195 offset1:203
	ds_read2_b32 v[16:17], v157 offset0:4 offset1:12
	ds_read2_b32 v[18:19], v157 offset0:69 offset1:77
	ds_read2_b32 v[20:21], v157 offset0:134 offset1:142
	ds_read2_b32 v[22:23], v157 offset0:199 offset1:207
	v_and_b32_e32 v27, 0xfc3, v26
	s_waitcnt lgkmcnt(0)
	v_cvt_pk_bf16_f32 v4, v10, v8
	v_or_b32_e32 v8, v27, v135
	v_lshrrev_b32_e32 v8, 3, v8
	v_and_or_b32 v8, v8, 10, v131
	v_lshlrev_b32_e32 v10, 6, v26
	v_and_b32_e32 v28, 0xc0, v10
	v_lshlrev_b32_e32 v8, 10, v8
	v_cvt_pk_bf16_f32 v5, v12, v14
	v_cvt_pk_bf16_f32 v6, v16, v18
	v_cvt_pk_bf16_f32 v7, v20, v22
	v_or3_b32 v24, v8, v28, v132
	global_store_dwordx4 v24, v[4:7], s[8:9] nt
	v_mov_b32_e32 v25, v3
	s_nop 0
	v_cvt_pk_bf16_f32 v4, v11, v9
	v_cvt_pk_bf16_f32 v5, v13, v15
	v_cvt_pk_bf16_f32 v6, v17, v19
	v_cvt_pk_bf16_f32 v7, v21, v23
	ds_read2_b32 v[8:9], v134 offset0:81 offset1:89
	ds_read2_b32 v[10:11], v134 offset0:16 offset1:24
	ds_read2_b32 v[12:13], v134 offset0:146 offset1:154
	ds_read2_b32 v[14:15], v134 offset0:211 offset1:219
	ds_read2_b32 v[16:17], v157 offset0:20 offset1:28
	ds_read2_b32 v[18:19], v157 offset0:85 offset1:93
	ds_read2_b32 v[20:21], v157 offset0:150 offset1:158
	ds_read2_b32 v[22:23], v157 offset0:215 offset1:223
	global_store_dwordx4 v24, v[4:7], s[8:9] offset:256 nt
	v_xor_b32_e32 v24, 32, v24
	v_lshl_add_u64 v[24:25], s[8:9], 0, v[24:25]
	s_waitcnt lgkmcnt(6)
	v_cvt_pk_bf16_f32 v4, v10, v8
	v_or_b32_e32 v8, v27, v133
	v_lshrrev_b32_e32 v8, 3, v8
	v_and_or_b32 v8, v8, 10, v131
	v_lshlrev_b32_e32 v8, 10, v8
	s_waitcnt lgkmcnt(4)
	v_cvt_pk_bf16_f32 v5, v12, v14
	s_waitcnt lgkmcnt(2)
	v_cvt_pk_bf16_f32 v6, v16, v18
	s_waitcnt lgkmcnt(0)
	v_cvt_pk_bf16_f32 v7, v20, v22
	v_or3_b32 v8, v8, v28, v132
	global_store_dwordx4 v[24:25], v[4:7], off offset:512 nt
	v_xor_b32_e32 v8, 32, v8
	s_nop 0
	v_cvt_pk_bf16_f32 v4, v11, v9
	v_mov_b32_e32 v9, v3
	v_cvt_pk_bf16_f32 v5, v13, v15
	v_cvt_pk_bf16_f32 v6, v17, v19
	v_cvt_pk_bf16_f32 v7, v21, v23
	v_lshl_add_u64 v[8:9], s[8:9], 0, v[8:9]
	ds_read2_b32 v[10:11], v134 offset0:32 offset1:40
	ds_read2_b32 v[12:13], v134 offset0:97 offset1:105
	ds_read2_b32 v[14:15], v134 offset0:162 offset1:170
	ds_read2_b32 v[16:17], v134 offset0:227 offset1:235
	ds_read2_b32 v[18:19], v157 offset0:36 offset1:44
	ds_read2_b32 v[20:21], v157 offset0:101 offset1:109
	ds_read2_b32 v[22:23], v157 offset0:166 offset1:174
	ds_read2_b32 v[24:25], v157 offset0:231 offset1:239
	global_store_dwordx4 v[8:9], v[4:7], off offset:768 nt
	v_add_u32_e32 v8, 32, v26
	v_and_or_b32 v9, v8, s74, v135
	v_lshrrev_b32_e32 v9, 3, v9
	v_and_or_b32 v9, v9, 14, v131
	v_lshlrev_b32_e32 v8, 6, v8
	v_and_b32_e32 v8, 0xc0, v8
	v_lshlrev_b32_e32 v9, 10, v9
	s_waitcnt lgkmcnt(6)
	v_cvt_pk_bf16_f32 v4, v10, v12
	s_waitcnt lgkmcnt(4)
	v_cvt_pk_bf16_f32 v5, v14, v16
	s_waitcnt lgkmcnt(2)
	v_cvt_pk_bf16_f32 v6, v18, v20
	s_waitcnt lgkmcnt(0)
	v_cvt_pk_bf16_f32 v7, v22, v24
	v_or3_b32 v8, v9, v8, v132
	global_store_dwordx4 v8, v[4:7], s[8:9] nt
	v_add_u32_e32 v8, 40, v26
	v_and_or_b32 v9, v8, s74, v135
	v_lshrrev_b32_e32 v9, 3, v9
	v_and_or_b32 v9, v9, 14, v131
	v_lshlrev_b32_e32 v8, 6, v8
	v_and_b32_e32 v8, 0xc0, v8
	v_lshlrev_b32_e32 v9, 10, v9
	v_cvt_pk_bf16_f32 v4, v11, v13
	v_cvt_pk_bf16_f32 v5, v15, v17
	v_cvt_pk_bf16_f32 v6, v19, v21
	v_cvt_pk_bf16_f32 v7, v23, v25
	v_or3_b32 v24, v9, v8, v132
	ds_read2_b32 v[8:9], v134 offset0:48 offset1:56
	ds_read2_b32 v[10:11], v134 offset0:113 offset1:121
	ds_read2_b32 v[12:13], v134 offset0:178 offset1:186
	ds_read2_b32 v[14:15], v134 offset0:243 offset1:251
	ds_read2_b32 v[16:17], v157 offset0:52 offset1:60
	ds_read2_b32 v[18:19], v157 offset0:117 offset1:125
	ds_read2_b32 v[20:21], v157 offset0:182 offset1:190
	ds_read2_b32 v[22:23], v157 offset0:247 offset1:255
	global_store_dwordx4 v24, v[4:7], s[8:9] offset:256 nt
	v_mov_b32_e32 v25, v3
	s_waitcnt lgkmcnt(6)
	v_cvt_pk_bf16_f32 v4, v8, v10
	v_add_u32_e32 v8, 48, v26
	v_and_or_b32 v10, v8, s74, v135
	v_lshrrev_b32_e32 v10, 3, v10
	v_and_or_b32 v10, v10, 14, v131
	v_lshlrev_b32_e32 v8, 6, v8
	v_and_b32_e32 v8, 0xc0, v8
	v_lshlrev_b32_e32 v10, 10, v10
	v_or3_b32 v8, v10, v8, v132
	v_xor_b32_e32 v24, 32, v8
	s_waitcnt lgkmcnt(4)
	v_cvt_pk_bf16_f32 v5, v12, v14
	s_waitcnt lgkmcnt(2)
	v_cvt_pk_bf16_f32 v6, v16, v18
	s_waitcnt lgkmcnt(0)
	v_cvt_pk_bf16_f32 v7, v20, v22
	v_lshl_add_u64 v[24:25], s[8:9], 0, v[24:25]
	v_add_u32_e32 v8, 56, v26
	global_store_dwordx4 v[24:25], v[4:7], off offset:512 nt
	s_nop 1
	v_cvt_pk_bf16_f32 v4, v9, v11
	v_and_or_b32 v9, v8, s74, v133
	v_lshrrev_b32_e32 v9, 3, v9
	v_and_or_b32 v9, v9, 14, v131
	v_lshlrev_b32_e32 v8, 6, v8
	v_and_b32_e32 v8, 0xc0, v8
	v_lshlrev_b32_e32 v9, 10, v9
	v_or3_b32 v8, v9, v8, v132
	v_xor_b32_e32 v8, 32, v8
	v_mov_b32_e32 v9, v3
	v_cvt_pk_bf16_f32 v5, v13, v15
	v_cvt_pk_bf16_f32 v6, v17, v19
	v_cvt_pk_bf16_f32 v7, v21, v23
	v_lshl_add_u64 v[8:9], s[8:9], 0, v[8:9]
	global_store_dwordx4 v[8:9], v[4:7], off offset:768 nt
	s_waitcnt lgkmcnt(0)
	s_mov_b64 s[8:9], 0
; __device__ __forceinline__ void transpose_item(const float* W, int ldw, bf16_t* WT, int ldt, int koff, int k0, int nsrc, int ndst, LAS float* scr, int lane) {
;     const float* src = W + (size_t)k0 * ldw + nsrc + lane;
; #pragma unroll 32
;     for (int kk = 0; kk < 64; ++kk) scr[kk * 65 + lane] = src[(size_t)kk * ldw];
; __device__ __forceinline__ void phase0(const Args& a, LAS unsigned char* lds, int bid, int G) {
;     ...
;         if (r < I_B) { const int kb = r >> 6, nb = r & 63; transpose_item(a.w_branch, DM, WbT, LDP, 0, 64 * kb, 64 * nb, 64 * nb, scr, lane); continue; } r -= I_B;
;         if (r < I_B) { const int kb = r >> 6, nb = r & 63; transpose_item(a.w_branch + (size_t)BW * DM, DM, WbT, LDP, BW, 64 * kb, 64 * nb, 64 * nb, scr, lane); continue; } r -= I_B;
;         { const int kb = r >> 6, nb = r & 63; transpose_item(a.w_out, DM, WoT, LDP, 0, 64 * kb, 64 * nb, 64 * nb, scr, lane); }
.LBB0_26:
	s_andn2_b64 vcc, exec, s[8:9]
	s_cbranch_vccnz .LBB0_28
	s_and_b32 s0, s12, 0x7fc0
	s_addk_i32 s0, 0x9800
	s_lshl_b64 s[8:9], s[0:1], 14
	v_readlane_b32 s0, v252, 20
	s_add_u32 s0, s0, s8
	v_readlane_b32 s8, v252, 21
	s_addc_u32 s9, s8, s9
	s_lshl_b32 s8, s10, 2
	s_add_u32 s8, s0, s8
	s_addc_u32 s9, s9, 0
	v_lshl_add_u64 v[4:5], s[8:9], 0, v[2:3]
	s_movk_i32 s0, 0x4000
	v_add_co_u32_e32 v8, vcc, s0, v4
	s_mov_b32 s0, 0x8000
	s_nop 0
	v_addc_co_u32_e32 v9, vcc, 0, v5, vcc
	v_add_co_u32_e32 v10, vcc, s0, v4
	s_mov_b32 s0, 0xc000
	s_nop 0
	v_addc_co_u32_e32 v11, vcc, 0, v5, vcc
	v_add_co_u32_e32 v12, vcc, s0, v4
	s_mov_b32 s0, 0x10000
	s_nop 0
	v_addc_co_u32_e32 v13, vcc, 0, v5, vcc
	v_add_co_u32_e32 v14, vcc, s0, v4
	s_mov_b32 s0, 0x14000
	s_nop 0
	v_addc_co_u32_e32 v15, vcc, 0, v5, vcc
	v_add_co_u32_e32 v16, vcc, s0, v4
	s_mov_b32 s0, 0x1c000
	s_nop 0
	v_addc_co_u32_e32 v17, vcc, 0, v5, vcc
	v_add_co_u32_e32 v18, vcc, s69, v4
	global_load_dword v6, v2, s[8:9] nt
	s_nop 0
	v_addc_co_u32_e32 v19, vcc, 0, v5, vcc
	v_add_co_u32_e32 v20, vcc, s0, v4
	s_mov_b32 s0, 0x20000
	s_nop 0
	v_addc_co_u32_e32 v21, vcc, 0, v5, vcc
	v_add_co_u32_e32 v22, vcc, s0, v4
	s_mov_b32 s0, 0x24000
	s_nop 0
	v_addc_co_u32_e32 v23, vcc, 0, v5, vcc
	global_load_dword v7, v[8:9], off nt
	s_nop 0
	global_load_dword v8, v[10:11], off nt
	global_load_dword v9, v[12:13], off nt
	s_nop 0
	global_load_dword v10, v[14:15], off nt
	global_load_dword v11, v[16:17], off nt
	global_load_dword v12, v[18:19], off nt
	global_load_dword v13, v[20:21], off nt
	s_nop 0
	global_load_dword v14, v[22:23], off nt
	v_add_co_u32_e32 v16, vcc, s0, v4
	s_mov_b32 s0, 0x28000
	s_nop 0
	v_addc_co_u32_e32 v17, vcc, 0, v5, vcc
	v_add_co_u32_e32 v18, vcc, s0, v4
	s_mov_b32 s0, 0x2c000
	s_nop 0
	v_addc_co_u32_e32 v19, vcc, 0, v5, vcc
	v_add_co_u32_e32 v20, vcc, s0, v4
	s_mov_b32 s0, 0x34000
	s_nop 0
	v_addc_co_u32_e32 v21, vcc, 0, v5, vcc
	v_add_co_u32_e32 v22, vcc, s75, v4
	s_and_b32 s8, s23, 0x7c0
	s_nop 0
	v_addc_co_u32_e32 v23, vcc, 0, v5, vcc
	v_add_co_u32_e32 v24, vcc, s0, v4
	s_mov_b32 s0, 0x38000
	s_nop 0
	v_addc_co_u32_e32 v25, vcc, 0, v5, vcc
	v_add_co_u32_e32 v26, vcc, s0, v4
	s_mov_b32 s0, 0x3c000
	s_nop 0
	v_addc_co_u32_e32 v27, vcc, 0, v5, vcc
	v_add_co_u32_e32 v28, vcc, s0, v4
	s_mov_b32 s0, 0x40000
	s_nop 0
	v_addc_co_u32_e32 v29, vcc, 0, v5, vcc
	v_add_co_u32_e32 v30, vcc, s0, v4
	s_mov_b32 s0, 0x44000
	s_nop 0
	v_addc_co_u32_e32 v31, vcc, 0, v5, vcc
	global_load_dword v15, v[16:17], off nt
	s_nop 0
	global_load_dword v16, v[18:19], off nt
	global_load_dword v17, v[20:21], off nt
	s_nop 0
	global_load_dword v18, v[22:23], off nt
	global_load_dword v19, v[24:25], off nt
	global_load_dword v20, v[26:27], off nt
	global_load_dword v21, v[28:29], off nt
	s_nop 0
	global_load_dword v22, v[30:31], off nt
	v_add_co_u32_e32 v24, vcc, s0, v4
	s_mov_b32 s0, 0x4c000
	s_nop 0
	v_addc_co_u32_e32 v25, vcc, 0, v5, vcc
	v_add_co_u32_e32 v26, vcc, s88, v4
	s_nop 1
	v_addc_co_u32_e32 v27, vcc, 0, v5, vcc
	v_add_co_u32_e32 v28, vcc, s0, v4
	s_mov_b32 s0, 0x50000
	s_nop 0
	v_addc_co_u32_e32 v29, vcc, 0, v5, vcc
	v_add_co_u32_e32 v30, vcc, s0, v4
	s_mov_b32 s0, 0x54000
	s_nop 0
	v_addc_co_u32_e32 v31, vcc, 0, v5, vcc
	v_add_co_u32_e32 v32, vcc, s0, v4
	s_mov_b32 s0, 0x58000
	s_nop 0
	v_addc_co_u32_e32 v33, vcc, 0, v5, vcc
	v_add_co_u32_e32 v34, vcc, s0, v4
	s_mov_b32 s0, 0x5c000
	s_nop 0
	v_addc_co_u32_e32 v35, vcc, 0, v5, vcc
	v_add_co_u32_e32 v36, vcc, s0, v4
	s_mov_b32 s0, 0x64000
	s_nop 0
	v_addc_co_u32_e32 v37, vcc, 0, v5, vcc
	v_add_co_u32_e32 v38, vcc, s89, v4
	s_nop 1
	v_addc_co_u32_e32 v39, vcc, 0, v5, vcc
	global_load_dword v23, v[24:25], off nt
	global_load_dword v40, v[26:27], off nt
	global_load_dword v41, v[28:29], off nt
	global_load_dword v42, v[30:31], off nt
	global_load_dword v43, v[32:33], off nt
	global_load_dword v44, v[34:35], off nt
	global_load_dword v45, v[36:37], off nt
	global_load_dword v46, v[38:39], off nt
	v_add_co_u32_e32 v24, vcc, s0, v4
	s_mov_b32 s0, 0x68000
	s_nop 0
	v_addc_co_u32_e32 v25, vcc, 0, v5, vcc
	v_add_co_u32_e32 v26, vcc, s0, v4
	s_add_i32 s0, s12, 0xffffa000
	s_nop 0
	v_addc_co_u32_e32 v27, vcc, 0, v5, vcc
	v_add_co_u32_e32 v28, vcc, s90, v4
	s_lshr_b32 s0, s0, 6
	s_nop 0
	v_addc_co_u32_e32 v29, vcc, 0, v5, vcc
	v_add_co_u32_e32 v30, vcc, s91, v4
	s_add_i32 s0, s8, s0
	s_nop 0
	v_addc_co_u32_e32 v31, vcc, 0, v5, vcc
	v_add_co_u32_e32 v32, vcc, s92, v4
	s_lshl_b64 s[8:9], s[0:1], 14
	s_nop 0
	v_addc_co_u32_e32 v33, vcc, 0, v5, vcc
	v_add_co_u32_e32 v34, vcc, s93, v4
	s_add_u32 s8, s16, s8
	s_nop 0
	v_addc_co_u32_e32 v35, vcc, 0, v5, vcc
	v_add_co_u32_e32 v36, vcc, s94, v4
	s_addc_u32 s9, s17, s9
	s_nop 0
	v_addc_co_u32_e32 v37, vcc, 0, v5, vcc
	v_add_co_u32_e32 v38, vcc, s95, v4
	s_nop 1
	v_addc_co_u32_e32 v39, vcc, 0, v5, vcc
	global_load_dword v47, v[24:25], off nt
	global_load_dword v48, v[26:27], off nt
	global_load_dword v49, v[28:29], off nt
	global_load_dword v50, v[30:31], off nt
	global_load_dword v51, v[32:33], off nt
	global_load_dword v52, v[34:35], off nt
	global_load_dword v53, v[36:37], off nt
	global_load_dword v54, v[38:39], off nt
	v_add_co_u32_e32 v24, vcc, s96, v4
	s_nop 1
	v_addc_co_u32_e32 v25, vcc, 0, v5, vcc
	v_add_co_u32_e32 v26, vcc, s97, v4
	s_nop 1
	v_addc_co_u32_e32 v27, vcc, 0, v5, vcc
	v_add_co_u32_e32 v28, vcc, s26, v4
	s_nop 1
	v_addc_co_u32_e32 v29, vcc, 0, v5, vcc
	v_add_co_u32_e32 v30, vcc, s27, v4
	s_nop 1
	v_addc_co_u32_e32 v31, vcc, 0, v5, vcc
	v_add_co_u32_e32 v32, vcc, s60, v4
	s_nop 1
	v_addc_co_u32_e32 v33, vcc, 0, v5, vcc
	v_add_co_u32_e32 v34, vcc, s61, v4
	s_nop 1
	v_addc_co_u32_e32 v35, vcc, 0, v5, vcc
; __device__ __forceinline__ void transpose_item(const float* W, int ldw, bf16_t* WT, int ldt, int koff, int k0, int nsrc, int ndst, LAS float* scr, int lane) {
;     const float* src = W + (size_t)k0 * ldw + nsrc + lane;
; #pragma unroll 32
;     for (int kk = 0; kk < 64; ++kk) scr[kk * 65 + lane] = src[(size_t)kk * ldw];
	v_add_co_u32_e32 v36, vcc, s52, v4
	s_nop 1
	v_addc_co_u32_e32 v37, vcc, 0, v5, vcc
	v_add_co_u32_e32 v38, vcc, s53, v4
	s_nop 1
	v_addc_co_u32_e32 v39, vcc, 0, v5, vcc
	global_load_dword v55, v[24:25], off nt
	global_load_dword v56, v[26:27], off nt
	global_load_dword v57, v[28:29], off nt
	global_load_dword v58, v[30:31], off nt
	global_load_dword v59, v[32:33], off nt
	global_load_dword v60, v[34:35], off nt
	global_load_dword v61, v[36:37], off nt
	global_load_dword v62, v[38:39], off nt
	v_add_co_u32_e32 v24, vcc, s54, v4
	s_nop 1
	v_addc_co_u32_e32 v25, vcc, 0, v5, vcc
	v_add_co_u32_e32 v26, vcc, s55, v4
	s_nop 1
	v_addc_co_u32_e32 v27, vcc, 0, v5, vcc
	v_add_co_u32_e32 v28, vcc, s56, v4
	s_nop 1
	v_addc_co_u32_e32 v29, vcc, 0, v5, vcc
	v_add_co_u32_e32 v30, vcc, s57, v4
	s_nop 1
	v_addc_co_u32_e32 v31, vcc, 0, v5, vcc
	v_add_co_u32_e32 v32, vcc, s58, v4
	s_nop 1
	v_addc_co_u32_e32 v33, vcc, 0, v5, vcc
	v_add_co_u32_e32 v34, vcc, s59, v4
	s_nop 1
	v_addc_co_u32_e32 v35, vcc, 0, v5, vcc
	v_add_co_u32_e32 v36, vcc, s18, v4
	s_nop 1
	v_addc_co_u32_e32 v37, vcc, 0, v5, vcc
	v_add_co_u32_e32 v38, vcc, s19, v4
	s_nop 1
	v_addc_co_u32_e32 v39, vcc, 0, v5, vcc
	global_load_dword v63, v[24:25], off nt
	global_load_dword v64, v[26:27], off nt
	global_load_dword v65, v[28:29], off nt
	global_load_dword v66, v[30:31], off nt
	global_load_dword v67, v[32:33], off nt
	global_load_dword v68, v[34:35], off nt
	global_load_dword v69, v[36:37], off nt
	global_load_dword v70, v[38:39], off nt
	v_add_co_u32_e32 v24, vcc, s21, v4
	s_nop 1
	v_addc_co_u32_e32 v25, vcc, 0, v5, vcc
	v_add_co_u32_e32 v26, vcc, s22, v4
	s_nop 1
	v_addc_co_u32_e32 v27, vcc, 0, v5, vcc
	v_add_co_u32_e32 v28, vcc, s3, v4
	s_nop 1
	v_addc_co_u32_e32 v29, vcc, 0, v5, vcc
	v_add_co_u32_e32 v30, vcc, s13, v4
	s_nop 1
	v_addc_co_u32_e32 v31, vcc, 0, v5, vcc
	v_add_co_u32_e32 v32, vcc, s34, v4
	s_nop 1
	v_addc_co_u32_e32 v33, vcc, 0, v5, vcc
	v_add_co_u32_e32 v34, vcc, s35, v4
	s_nop 1
	v_addc_co_u32_e32 v35, vcc, 0, v5, vcc
	v_add_co_u32_e32 v36, vcc, s64, v4
	s_nop 1
	v_addc_co_u32_e32 v37, vcc, 0, v5, vcc
	v_add_co_u32_e32 v38, vcc, s65, v4
	s_nop 1
	v_addc_co_u32_e32 v39, vcc, 0, v5, vcc
	global_load_dword v71, v[24:25], off nt
	global_load_dword v72, v[26:27], off nt
	global_load_dword v73, v[28:29], off nt
	global_load_dword v74, v[30:31], off nt
	global_load_dword v75, v[32:33], off nt
	global_load_dword v76, v[34:35], off nt
	s_nop 0
	global_load_dword v36, v[36:37], off nt
	s_nop 0
	global_load_dword v37, v[38:39], off nt
	v_add_co_u32_e32 v24, vcc, s66, v4
	s_nop 1
	v_addc_co_u32_e32 v25, vcc, 0, v5, vcc
	v_add_co_u32_e32 v26, vcc, s67, v4
	s_nop 1
	v_addc_co_u32_e32 v27, vcc, 0, v5, vcc
	v_add_co_u32_e32 v28, vcc, s68, v4
	s_nop 1
	v_addc_co_u32_e32 v29, vcc, 0, v5, vcc
	v_add_co_u32_e32 v30, vcc, s70, v4
	s_nop 1
	v_addc_co_u32_e32 v31, vcc, 0, v5, vcc
	v_add_co_u32_e32 v32, vcc, s71, v4
	s_nop 1
	v_addc_co_u32_e32 v33, vcc, 0, v5, vcc
	v_add_co_u32_e32 v34, vcc, s72, v4
	s_nop 1
	v_addc_co_u32_e32 v35, vcc, 0, v5, vcc
	v_add_co_u32_e32 v4, vcc, s73, v4
	s_nop 1
	v_addc_co_u32_e32 v5, vcc, 0, v5, vcc
	global_load_dword v24, v[24:25], off nt
	s_nop 0
	global_load_dword v25, v[26:27], off nt
	s_nop 0
	global_load_dword v26, v[28:29], off nt
	global_load_dword v27, v[30:31], off nt
	s_nop 0
	global_load_dword v28, v[32:33], off nt
	global_load_dword v29, v[34:35], off nt
	s_nop 0
	global_load_dword v4, v[4:5], off nt
	s_waitcnt vmcnt(62)
	ds_write2_b32 v1, v6, v7 offset1:65
	s_waitcnt vmcnt(60)
	ds_write2_b32 v1, v8, v9 offset0:130 offset1:195
	s_waitcnt vmcnt(58)
	ds_write2_b32 v142, v10, v11 offset0:4 offset1:69
	s_waitcnt vmcnt(56)
	ds_write2_b32 v142, v12, v13 offset0:134 offset1:199
	s_waitcnt vmcnt(54)
	ds_write2_b32 v143, v14, v15 offset0:8 offset1:73
	s_waitcnt vmcnt(52)
	ds_write2_b32 v143, v16, v17 offset0:138 offset1:203
	s_waitcnt vmcnt(50)
	ds_write2_b32 v144, v18, v19 offset0:12 offset1:77
	s_waitcnt vmcnt(48)
	ds_write2_b32 v144, v20, v21 offset0:142 offset1:207
	s_waitcnt vmcnt(46)
	ds_write2_b32 v145, v22, v23 offset0:16 offset1:81
	s_waitcnt vmcnt(44)
	ds_write2_b32 v145, v40, v41 offset0:146 offset1:211
	s_waitcnt vmcnt(42)
	ds_write2_b32 v146, v42, v43 offset0:20 offset1:85
	s_waitcnt vmcnt(40)
	ds_write2_b32 v146, v44, v45 offset0:150 offset1:215
	s_waitcnt vmcnt(38)
	ds_write2_b32 v147, v46, v47 offset0:24 offset1:89
	s_waitcnt vmcnt(36)
	ds_write2_b32 v147, v48, v49 offset0:154 offset1:219
	s_waitcnt vmcnt(34)
	ds_write2_b32 v148, v50, v51 offset0:28 offset1:93
	s_waitcnt vmcnt(32)
	ds_write2_b32 v148, v52, v53 offset0:158 offset1:223
	s_waitcnt vmcnt(30)
	ds_write2_b32 v149, v54, v55 offset0:32 offset1:97
	s_waitcnt vmcnt(28)
	ds_write2_b32 v149, v56, v57 offset0:162 offset1:227
	s_waitcnt vmcnt(26)
	ds_write2_b32 v150, v58, v59 offset0:36 offset1:101
	s_waitcnt vmcnt(24)
	ds_write2_b32 v150, v60, v61 offset0:166 offset1:231
	s_waitcnt vmcnt(22)
	ds_write2_b32 v151, v62, v63 offset0:40 offset1:105
	s_waitcnt vmcnt(20)
	ds_write2_b32 v151, v64, v65 offset0:170 offset1:235
	s_waitcnt vmcnt(18)
	ds_write2_b32 v152, v66, v67 offset0:44 offset1:109
	s_waitcnt vmcnt(16)
	ds_write2_b32 v152, v68, v69 offset0:174 offset1:239
	s_waitcnt vmcnt(14)
	ds_write2_b32 v153, v70, v71 offset0:48 offset1:113
	s_waitcnt vmcnt(12)
	ds_write2_b32 v153, v72, v73 offset0:178 offset1:243
	s_waitcnt vmcnt(10)
	ds_write2_b32 v154, v74, v75 offset0:52 offset1:117
	s_waitcnt vmcnt(8)
; #define LAS __attribute__((address_space(3)))
; __device__ __forceinline__ unsigned pk2(float lo, float hi) { return __builtin_bit_cast(unsigned, __builtin_convertvector((f32x2){lo, hi}, bf16x2_t)); }
; #define LDS_WAIT() asm volatile("s_waitcnt lgkmcnt(0)" ::: "memory")
; __device__ __forceinline__ void transpose_item(const float* W, int ldw, bf16_t* WT, int ldt, int koff, int k0, int nsrc, int ndst, LAS float* scr, int lane) {
;     ...
;     for (int kk = 0; kk < 64; ++kk) scr[kk * 65 + lane] = src[(size_t)kk * ldw];
;     LDS_WAIT(); asm volatile("" ::: "memory");
;     const int c = lane & 7;
; #pragma unroll
;     for (int j = 0; j < 8; ++j) { const int n = (lane >> 3) + 8 * j; const LAS float* s = scr + (8 * c) * 65 + n;
;         u32x4 o; o.x = pk2(s[0 * 65], s[1 * 65]); o.y = pk2(s[2 * 65], s[3 * 65]); o.z = pk2(s[4 * 65], s[5 * 65]); o.w = pk2(s[6 * 65], s[7 * 65]);
;         *(u32x4*)((char*)WT + tiled_off_b(ndst + n, koff + k0 + 8 * c)) = o; }
;     LDS_WAIT(); asm volatile("" ::: "memory");
	ds_write2_b32 v154, v76, v36 offset0:182 offset1:247
	s_waitcnt vmcnt(6)
	ds_write2_b32 v155, v37, v24 offset0:56 offset1:121
	s_waitcnt vmcnt(4)
	ds_write2_b32 v155, v25, v26 offset0:186 offset1:251
	s_waitcnt vmcnt(2)
	ds_write2_b32 v156, v27, v28 offset0:60 offset1:125
	s_waitcnt vmcnt(0)
	ds_write2_b32 v156, v29, v4 offset0:190 offset1:255
	s_waitcnt lgkmcnt(0)
	ds_read2_b32 v[8:9], v134 offset0:65 offset1:73
	ds_read2_b32 v[10:11], v134 offset1:8
	ds_read2_b32 v[12:13], v134 offset0:130 offset1:138
	ds_read2_b32 v[14:15], v134 offset0:195 offset1:203
	ds_read2_b32 v[16:17], v157 offset0:4 offset1:12
	ds_read2_b32 v[18:19], v157 offset0:69 offset1:77
	ds_read2_b32 v[20:21], v157 offset0:134 offset1:142
	ds_read2_b32 v[22:23], v157 offset0:199 offset1:207
	s_waitcnt lgkmcnt(0)
	v_cvt_pk_bf16_f32 v4, v10, v8
	v_add_u32_e32 v8, s25, v135
	v_lshrrev_b32_e32 v8, 3, v8
	v_and_or_b32 v8, v8, 10, v131
	v_lshlrev_b32_e32 v8, 10, v8
	v_cvt_pk_bf16_f32 v5, v12, v14
	v_cvt_pk_bf16_f32 v6, v16, v18
	v_cvt_pk_bf16_f32 v7, v20, v22
	v_or_b32_e32 v24, v8, v136
	global_store_dwordx4 v24, v[4:7], s[8:9] nt
	v_or_b32_e32 v25, v8, v137
	v_xor_b32_e32 v24, 32, v24
	v_cvt_pk_bf16_f32 v4, v11, v9
	v_cvt_pk_bf16_f32 v5, v13, v15
	v_cvt_pk_bf16_f32 v6, v17, v19
	v_cvt_pk_bf16_f32 v7, v21, v23
	ds_read2_b32 v[8:9], v134 offset0:16 offset1:24
	ds_read2_b32 v[10:11], v134 offset0:81 offset1:89
	ds_read2_b32 v[12:13], v134 offset0:146 offset1:154
	ds_read2_b32 v[14:15], v134 offset0:211 offset1:219
	ds_read2_b32 v[16:17], v157 offset0:20 offset1:28
	ds_read2_b32 v[18:19], v157 offset0:85 offset1:93
	ds_read2_b32 v[20:21], v157 offset0:150 offset1:158
	ds_read2_b32 v[22:23], v157 offset0:215 offset1:223
	global_store_dwordx4 v25, v[4:7], s[8:9] nt
	v_mov_b32_e32 v25, v3
	v_lshl_add_u64 v[24:25], s[8:9], 0, v[24:25]
	s_waitcnt lgkmcnt(6)
	v_cvt_pk_bf16_f32 v4, v8, v10
	v_add_u32_e32 v8, s25, v133
	v_lshrrev_b32_e32 v8, 3, v8
	v_and_or_b32 v8, v8, 10, v131
	s_waitcnt lgkmcnt(4)
	v_cvt_pk_bf16_f32 v5, v12, v14
	s_waitcnt lgkmcnt(2)
	v_cvt_pk_bf16_f32 v6, v16, v18
	s_waitcnt lgkmcnt(0)
	v_cvt_pk_bf16_f32 v7, v20, v22
	v_lshl_or_b32 v8, v8, 10, v136
	global_store_dwordx4 v[24:25], v[4:7], off offset:512 nt
	v_xor_b32_e32 v8, 32, v8
	v_add_u32_e32 v26, s25, v130
	v_cvt_pk_bf16_f32 v4, v9, v11
	v_mov_b32_e32 v9, v3
	v_cvt_pk_bf16_f32 v5, v13, v15
	v_cvt_pk_bf16_f32 v6, v17, v19
	v_cvt_pk_bf16_f32 v7, v21, v23
	v_lshl_add_u64 v[8:9], s[8:9], 0, v[8:9]
	ds_read2_b32 v[10:11], v134 offset0:32 offset1:40
	ds_read2_b32 v[12:13], v134 offset0:97 offset1:105
	ds_read2_b32 v[14:15], v134 offset0:162 offset1:170
	ds_read2_b32 v[16:17], v134 offset0:227 offset1:235
	ds_read2_b32 v[18:19], v157 offset0:36 offset1:44
	ds_read2_b32 v[20:21], v157 offset0:101 offset1:109
	ds_read2_b32 v[22:23], v157 offset0:166 offset1:174
	ds_read2_b32 v[24:25], v157 offset0:231 offset1:239
	global_store_dwordx4 v[8:9], v[4:7], off offset:768 nt
	v_add_u32_e32 v8, 32, v26
	v_and_or_b32 v9, v8, s74, v135
	v_lshrrev_b32_e32 v9, 3, v9
	v_and_or_b32 v9, v9, 14, v131
	v_lshlrev_b32_e32 v8, 6, v8
	v_and_b32_e32 v8, 0xc0, v8
	v_lshlrev_b32_e32 v9, 10, v9
	s_waitcnt lgkmcnt(6)
	v_cvt_pk_bf16_f32 v4, v10, v12
	s_waitcnt lgkmcnt(4)
	v_cvt_pk_bf16_f32 v5, v14, v16
	s_waitcnt lgkmcnt(2)
	v_cvt_pk_bf16_f32 v6, v18, v20
	s_waitcnt lgkmcnt(0)
	v_cvt_pk_bf16_f32 v7, v22, v24
	v_or3_b32 v8, v9, v8, v132
	global_store_dwordx4 v8, v[4:7], s[8:9] nt
	v_add_u32_e32 v8, 40, v26
	v_and_or_b32 v9, v8, s74, v135
	v_lshrrev_b32_e32 v9, 3, v9
	v_and_or_b32 v9, v9, 14, v131
	v_lshlrev_b32_e32 v8, 6, v8
	v_and_b32_e32 v8, 0xc0, v8
	v_lshlrev_b32_e32 v9, 10, v9
	v_cvt_pk_bf16_f32 v4, v11, v13
	v_cvt_pk_bf16_f32 v5, v15, v17
	v_cvt_pk_bf16_f32 v6, v19, v21
	v_cvt_pk_bf16_f32 v7, v23, v25
	v_or3_b32 v24, v9, v8, v132
	ds_read2_b32 v[8:9], v134 offset0:48 offset1:56
	ds_read2_b32 v[10:11], v134 offset0:113 offset1:121
	ds_read2_b32 v[12:13], v134 offset0:178 offset1:186
	ds_read2_b32 v[14:15], v134 offset0:243 offset1:251
	ds_read2_b32 v[16:17], v157 offset0:52 offset1:60
	ds_read2_b32 v[18:19], v157 offset0:117 offset1:125
	ds_read2_b32 v[20:21], v157 offset0:182 offset1:190
	ds_read2_b32 v[22:23], v157 offset0:247 offset1:255
	global_store_dwordx4 v24, v[4:7], s[8:9] offset:256 nt
	v_mov_b32_e32 v25, v3
	s_waitcnt lgkmcnt(6)
	v_cvt_pk_bf16_f32 v4, v8, v10
	v_add_u32_e32 v8, 48, v26
	v_and_or_b32 v10, v8, s74, v135
	v_lshrrev_b32_e32 v10, 3, v10
	v_and_or_b32 v10, v10, 14, v131
	v_lshlrev_b32_e32 v8, 6, v8
	v_and_b32_e32 v8, 0xc0, v8
	v_lshlrev_b32_e32 v10, 10, v10
	v_or3_b32 v8, v10, v8, v132
	v_xor_b32_e32 v24, 32, v8
	s_waitcnt lgkmcnt(4)
	v_cvt_pk_bf16_f32 v5, v12, v14
	s_waitcnt lgkmcnt(2)
	v_cvt_pk_bf16_f32 v6, v16, v18
	s_waitcnt lgkmcnt(0)
	v_cvt_pk_bf16_f32 v7, v20, v22
	v_lshl_add_u64 v[24:25], s[8:9], 0, v[24:25]
	v_add_u32_e32 v8, 56, v26
	global_store_dwordx4 v[24:25], v[4:7], off offset:512 nt
	s_nop 1
	v_cvt_pk_bf16_f32 v4, v9, v11
	v_and_or_b32 v9, v8, s74, v133
	v_lshrrev_b32_e32 v9, 3, v9
	v_and_or_b32 v9, v9, 14, v131
	v_lshlrev_b32_e32 v8, 6, v8
	v_and_b32_e32 v8, 0xc0, v8
	v_lshlrev_b32_e32 v9, 10, v9
	v_or3_b32 v8, v9, v8, v132
	v_xor_b32_e32 v8, 32, v8
	v_mov_b32_e32 v9, v3
	v_cvt_pk_bf16_f32 v5, v13, v15
	v_cvt_pk_bf16_f32 v6, v17, v19
	v_cvt_pk_bf16_f32 v7, v21, v23
	v_lshl_add_u64 v[8:9], s[8:9], 0, v[8:9]
	global_store_dwordx4 v[8:9], v[4:7], off offset:768 nt
	s_waitcnt lgkmcnt(0)

; __device__ __forceinline__ void transpose_item(const float* W, int ldw, bf16_t* WT, int ldt, int koff, int k0, int nsrc, int ndst, LAS float* scr, int lane) {
;     const float* src = W + (size_t)k0 * ldw + nsrc + lane;
; #pragma unroll 32
;     for (int kk = 0; kk < 64; ++kk) scr[kk * 65 + lane] = src[(size_t)kk * ldw];
; __device__ __forceinline__ void phase0(const Args& a, LAS unsigned char* lds, int bid, int G) {
;     ...
;         if (r < I_IN) { const int kb = r / 384, nb = r - kb * 384; transpose_item(a.w_in, PC, WinT, LDP, 0, 64 * kb, proj_src_col(64 * nb), 64 * nb, scr, lane); continue; } r -= I_IN;
;         if (r < I_B) { const int kb = r >> 6, nb = r & 63; transpose_item(a.w_branch, DM, WbT, LDP, 0, 64 * kb, 64 * nb, 64 * nb, scr, lane); continue; } r -= I_B;
;         if (r < I_B) { const int kb = r >> 6, nb = r & 63; transpose_item(a.w_branch + (size_t)BW * DM, DM, WbT, LDP, BW, 64 * kb, 64 * nb, 64 * nb, scr, lane); continue; } r -= I_B;
.LBB0_29:
	s_andn2_b64 vcc, exec, s[8:9]
	s_cbranch_vccnz .LBB0_31
	s_and_b32 s0, s12, 0x7fc0
	s_addk_i32 s0, 0xa000
	v_readlane_b32 s80, v252, 0
	s_and_b32 s10, s25, 0xfc0
	s_lshl_b64 s[8:9], s[0:1], 14
	v_readlane_b32 s82, v252, 2
	v_readlane_b32 s83, v252, 3
	s_add_u32 s8, s82, s8
	s_addc_u32 s9, s83, s9
	s_lshl_b32 s10, s10, 2
	s_add_u32 s8, s8, s10
	s_addc_u32 s9, s9, 0
	v_lshl_add_u64 v[4:5], s[8:9], 0, v[2:3]
	global_load_dword v6, v2, s[8:9] nt
	s_movk_i32 s8, 0x4000
	v_add_co_u32_e32 v8, vcc, s8, v4
	s_mov_b32 s8, 0x8000
	s_nop 0
	v_addc_co_u32_e32 v9, vcc, 0, v5, vcc
	v_add_co_u32_e32 v10, vcc, s8, v4
	s_mov_b32 s8, 0xc000
	s_nop 0
	v_addc_co_u32_e32 v11, vcc, 0, v5, vcc
	v_add_co_u32_e32 v12, vcc, s8, v4
	s_mov_b32 s8, 0x10000
	s_nop 0
	v_addc_co_u32_e32 v13, vcc, 0, v5, vcc
	v_add_co_u32_e32 v14, vcc, s8, v4
	s_mov_b32 s8, 0x14000
	s_nop 0
	v_addc_co_u32_e32 v15, vcc, 0, v5, vcc
	v_add_co_u32_e32 v16, vcc, s8, v4
	s_mov_b32 s8, 0x1c000
	s_nop 0
	v_addc_co_u32_e32 v17, vcc, 0, v5, vcc
	v_add_co_u32_e32 v18, vcc, s69, v4
	s_lshr_b32 s0, s0, 6
	s_nop 0
	v_addc_co_u32_e32 v19, vcc, 0, v5, vcc
	v_add_co_u32_e32 v20, vcc, s8, v4
	s_mov_b32 s8, 0x20000
	s_nop 0
	v_addc_co_u32_e32 v21, vcc, 0, v5, vcc
	v_add_co_u32_e32 v22, vcc, s8, v4
	s_mov_b32 s8, 0x24000
	s_nop 0
	v_addc_co_u32_e32 v23, vcc, 0, v5, vcc
	global_load_dword v7, v[8:9], off nt
	s_nop 0
	global_load_dword v8, v[10:11], off nt
	global_load_dword v9, v[12:13], off nt
	s_nop 0
	global_load_dword v10, v[14:15], off nt
	global_load_dword v11, v[16:17], off nt
	global_load_dword v12, v[18:19], off nt
	global_load_dword v13, v[20:21], off nt
	s_nop 0
	global_load_dword v14, v[22:23], off nt
	v_add_co_u32_e32 v16, vcc, s8, v4
	s_mov_b32 s8, 0x28000
	s_nop 0
	v_addc_co_u32_e32 v17, vcc, 0, v5, vcc
	v_add_co_u32_e32 v18, vcc, s8, v4
	s_mov_b32 s8, 0x2c000
	s_nop 0
	v_addc_co_u32_e32 v19, vcc, 0, v5, vcc
	v_add_co_u32_e32 v20, vcc, s8, v4
	s_mov_b32 s8, 0x34000
	s_nop 0
	v_addc_co_u32_e32 v21, vcc, 0, v5, vcc
	v_add_co_u32_e32 v22, vcc, s75, v4
	v_readlane_b32 s81, v252, 1
	s_nop 0
	v_addc_co_u32_e32 v23, vcc, 0, v5, vcc
	v_add_co_u32_e32 v24, vcc, s8, v4
	s_mov_b32 s8, 0x38000
	s_nop 0
	v_addc_co_u32_e32 v25, vcc, 0, v5, vcc
	v_add_co_u32_e32 v26, vcc, s8, v4
	s_mov_b32 s8, 0x3c000
	s_nop 0
	v_addc_co_u32_e32 v27, vcc, 0, v5, vcc
	v_add_co_u32_e32 v28, vcc, s8, v4
	s_mov_b32 s8, 0x40000
	s_nop 0
	v_addc_co_u32_e32 v29, vcc, 0, v5, vcc
	v_add_co_u32_e32 v30, vcc, s8, v4
	s_mov_b32 s8, 0x44000
	s_nop 0
	v_addc_co_u32_e32 v31, vcc, 0, v5, vcc
	global_load_dword v15, v[16:17], off nt
	s_nop 0
	global_load_dword v16, v[18:19], off nt
	global_load_dword v17, v[20:21], off nt
	s_nop 0
	global_load_dword v18, v[22:23], off nt
	global_load_dword v19, v[24:25], off nt
	global_load_dword v20, v[26:27], off nt
	global_load_dword v21, v[28:29], off nt
	s_nop 0
	global_load_dword v22, v[30:31], off nt
	v_add_co_u32_e32 v24, vcc, s8, v4
	s_mov_b32 s8, 0x4c000
	s_nop 0
	v_addc_co_u32_e32 v25, vcc, 0, v5, vcc
	v_add_co_u32_e32 v26, vcc, s88, v4
	v_readlane_b32 s84, v252, 4
	s_nop 0
	v_addc_co_u32_e32 v27, vcc, 0, v5, vcc
	v_add_co_u32_e32 v28, vcc, s8, v4
	s_mov_b32 s8, 0x50000
	s_nop 0
	v_addc_co_u32_e32 v29, vcc, 0, v5, vcc
	v_add_co_u32_e32 v30, vcc, s8, v4
	s_mov_b32 s8, 0x54000
	s_nop 0
	v_addc_co_u32_e32 v31, vcc, 0, v5, vcc
	v_add_co_u32_e32 v32, vcc, s8, v4
	s_mov_b32 s8, 0x58000
	s_nop 0
	v_addc_co_u32_e32 v33, vcc, 0, v5, vcc
	v_add_co_u32_e32 v34, vcc, s8, v4
	s_mov_b32 s8, 0x5c000
	s_nop 0
	v_addc_co_u32_e32 v35, vcc, 0, v5, vcc
	v_add_co_u32_e32 v36, vcc, s8, v4
	s_mov_b32 s8, 0x64000
	s_nop 0
	v_addc_co_u32_e32 v37, vcc, 0, v5, vcc
	v_add_co_u32_e32 v38, vcc, s89, v4
	v_readlane_b32 s85, v252, 5
	s_nop 0
	v_addc_co_u32_e32 v39, vcc, 0, v5, vcc
	global_load_dword v23, v[24:25], off nt
	global_load_dword v40, v[26:27], off nt
	global_load_dword v41, v[28:29], off nt
	global_load_dword v42, v[30:31], off nt
	global_load_dword v43, v[32:33], off nt
	global_load_dword v44, v[34:35], off nt
	global_load_dword v45, v[36:37], off nt
	global_load_dword v46, v[38:39], off nt
	v_add_co_u32_e32 v24, vcc, s8, v4
	s_mov_b32 s8, 0x68000
	s_nop 0
	v_addc_co_u32_e32 v25, vcc, 0, v5, vcc
	v_add_co_u32_e32 v26, vcc, s8, v4
	s_and_b32 s8, s23, 0x7c0
	s_nop 0
	v_addc_co_u32_e32 v27, vcc, 0, v5, vcc
	v_add_co_u32_e32 v28, vcc, s90, v4
	s_add_i32 s0, s0, s8
	s_nop 0
	v_addc_co_u32_e32 v29, vcc, 0, v5, vcc
	v_add_co_u32_e32 v30, vcc, s91, v4
	s_lshl_b64 s[8:9], s[0:1], 14
	s_nop 0
	v_addc_co_u32_e32 v31, vcc, 0, v5, vcc
	v_add_co_u32_e32 v32, vcc, s92, v4
	s_add_u32 s8, s16, s8
	s_nop 0
	v_addc_co_u32_e32 v33, vcc, 0, v5, vcc
	v_add_co_u32_e32 v34, vcc, s93, v4
	s_addc_u32 s9, s17, s9
	s_nop 0
	v_addc_co_u32_e32 v35, vcc, 0, v5, vcc
	v_add_co_u32_e32 v36, vcc, s94, v4
	v_readlane_b32 s86, v252, 6
	s_nop 0
	v_addc_co_u32_e32 v37, vcc, 0, v5, vcc
	v_add_co_u32_e32 v38, vcc, s95, v4
	v_readlane_b32 s87, v252, 7
	s_nop 0
	v_addc_co_u32_e32 v39, vcc, 0, v5, vcc
	global_load_dword v47, v[24:25], off nt
	global_load_dword v48, v[26:27], off nt
	global_load_dword v49, v[28:29], off nt
	global_load_dword v50, v[30:31], off nt
	global_load_dword v51, v[32:33], off nt
	global_load_dword v52, v[34:35], off nt
	global_load_dword v53, v[36:37], off nt
	global_load_dword v54, v[38:39], off nt
	v_add_co_u32_e32 v24, vcc, s96, v4
	s_nop 1
	v_addc_co_u32_e32 v25, vcc, 0, v5, vcc
	v_add_co_u32_e32 v26, vcc, s97, v4
	s_nop 1
	v_addc_co_u32_e32 v27, vcc, 0, v5, vcc
	v_add_co_u32_e32 v28, vcc, s26, v4
	s_nop 1
	v_addc_co_u32_e32 v29, vcc, 0, v5, vcc
	v_add_co_u32_e32 v30, vcc, s27, v4
	s_nop 1
	v_addc_co_u32_e32 v31, vcc, 0, v5, vcc
; __device__ __forceinline__ void transpose_item(const float* W, int ldw, bf16_t* WT, int ldt, int koff, int k0, int nsrc, int ndst, LAS float* scr, int lane) {
;     const float* src = W + (size_t)k0 * ldw + nsrc + lane;
; #pragma unroll 32
;     for (int kk = 0; kk < 64; ++kk) scr[kk * 65 + lane] = src[(size_t)kk * ldw];
	v_add_co_u32_e32 v32, vcc, s60, v4
	s_nop 1
	v_addc_co_u32_e32 v33, vcc, 0, v5, vcc
	v_add_co_u32_e32 v34, vcc, s61, v4
	s_nop 1
	v_addc_co_u32_e32 v35, vcc, 0, v5, vcc
	v_add_co_u32_e32 v36, vcc, s52, v4
	s_nop 1
	v_addc_co_u32_e32 v37, vcc, 0, v5, vcc
	v_add_co_u32_e32 v38, vcc, s53, v4
	s_nop 1
	v_addc_co_u32_e32 v39, vcc, 0, v5, vcc
	global_load_dword v55, v[24:25], off nt
	global_load_dword v56, v[26:27], off nt
	global_load_dword v57, v[28:29], off nt
	global_load_dword v58, v[30:31], off nt
	global_load_dword v59, v[32:33], off nt
	global_load_dword v60, v[34:35], off nt
	global_load_dword v61, v[36:37], off nt
	global_load_dword v62, v[38:39], off nt
	v_add_co_u32_e32 v24, vcc, s54, v4
	s_nop 1
	v_addc_co_u32_e32 v25, vcc, 0, v5, vcc
	v_add_co_u32_e32 v26, vcc, s55, v4
	s_nop 1
	v_addc_co_u32_e32 v27, vcc, 0, v5, vcc
	v_add_co_u32_e32 v28, vcc, s56, v4
	s_nop 1
	v_addc_co_u32_e32 v29, vcc, 0, v5, vcc
	v_add_co_u32_e32 v30, vcc, s57, v4
	s_nop 1
	v_addc_co_u32_e32 v31, vcc, 0, v5, vcc
	v_add_co_u32_e32 v32, vcc, s58, v4
	s_nop 1
	v_addc_co_u32_e32 v33, vcc, 0, v5, vcc
	v_add_co_u32_e32 v34, vcc, s59, v4
	s_nop 1
	v_addc_co_u32_e32 v35, vcc, 0, v5, vcc
	v_add_co_u32_e32 v36, vcc, s18, v4
	s_nop 1
	v_addc_co_u32_e32 v37, vcc, 0, v5, vcc
	v_add_co_u32_e32 v38, vcc, s19, v4
	s_nop 1
	v_addc_co_u32_e32 v39, vcc, 0, v5, vcc
	global_load_dword v63, v[24:25], off nt
	global_load_dword v64, v[26:27], off nt
	global_load_dword v65, v[28:29], off nt
	global_load_dword v66, v[30:31], off nt
	global_load_dword v67, v[32:33], off nt
	global_load_dword v68, v[34:35], off nt
	global_load_dword v69, v[36:37], off nt
	global_load_dword v70, v[38:39], off nt
	v_add_co_u32_e32 v24, vcc, s21, v4
	s_nop 1
	v_addc_co_u32_e32 v25, vcc, 0, v5, vcc
	v_add_co_u32_e32 v26, vcc, s22, v4
	s_nop 1
	v_addc_co_u32_e32 v27, vcc, 0, v5, vcc
	v_add_co_u32_e32 v28, vcc, s3, v4
	s_nop 1
	v_addc_co_u32_e32 v29, vcc, 0, v5, vcc
	v_add_co_u32_e32 v30, vcc, s13, v4
	s_nop 1
	v_addc_co_u32_e32 v31, vcc, 0, v5, vcc
	v_add_co_u32_e32 v32, vcc, s34, v4
	s_nop 1
	v_addc_co_u32_e32 v33, vcc, 0, v5, vcc
	v_add_co_u32_e32 v34, vcc, s35, v4
	s_nop 1
	v_addc_co_u32_e32 v35, vcc, 0, v5, vcc
	v_add_co_u32_e32 v36, vcc, s64, v4
	s_nop 1
	v_addc_co_u32_e32 v37, vcc, 0, v5, vcc
	v_add_co_u32_e32 v38, vcc, s65, v4
	s_nop 1
	v_addc_co_u32_e32 v39, vcc, 0, v5, vcc
	global_load_dword v71, v[24:25], off nt
	global_load_dword v72, v[26:27], off nt
	global_load_dword v73, v[28:29], off nt
	global_load_dword v74, v[30:31], off nt
	global_load_dword v75, v[32:33], off nt
	global_load_dword v76, v[34:35], off nt
	s_nop 0
	global_load_dword v36, v[36:37], off nt
	s_nop 0
	global_load_dword v37, v[38:39], off nt
	v_add_co_u32_e32 v24, vcc, s66, v4
	s_nop 1
	v_addc_co_u32_e32 v25, vcc, 0, v5, vcc
	v_add_co_u32_e32 v26, vcc, s67, v4
	s_nop 1
	v_addc_co_u32_e32 v27, vcc, 0, v5, vcc
	v_add_co_u32_e32 v28, vcc, s68, v4
	s_nop 1
	v_addc_co_u32_e32 v29, vcc, 0, v5, vcc
	v_add_co_u32_e32 v30, vcc, s70, v4
	s_nop 1
	v_addc_co_u32_e32 v31, vcc, 0, v5, vcc
	v_add_co_u32_e32 v32, vcc, s71, v4
	s_nop 1
	v_addc_co_u32_e32 v33, vcc, 0, v5, vcc
	v_add_co_u32_e32 v34, vcc, s72, v4
	s_nop 1
	v_addc_co_u32_e32 v35, vcc, 0, v5, vcc
	v_add_co_u32_e32 v4, vcc, s73, v4
	s_nop 1
	v_addc_co_u32_e32 v5, vcc, 0, v5, vcc
	global_load_dword v24, v[24:25], off nt
	s_nop 0
	global_load_dword v25, v[26:27], off nt
	s_nop 0
	global_load_dword v26, v[28:29], off nt
	global_load_dword v27, v[30:31], off nt
	s_nop 0
	global_load_dword v28, v[32:33], off nt
	global_load_dword v29, v[34:35], off nt
	s_nop 0
	global_load_dword v4, v[4:5], off nt
	s_waitcnt vmcnt(62)
	ds_write2_b32 v1, v6, v7 offset1:65
	s_waitcnt vmcnt(60)
	ds_write2_b32 v1, v8, v9 offset0:130 offset1:195
	s_waitcnt vmcnt(58)
	ds_write2_b32 v142, v10, v11 offset0:4 offset1:69
	s_waitcnt vmcnt(56)
	ds_write2_b32 v142, v12, v13 offset0:134 offset1:199
	s_waitcnt vmcnt(54)
	ds_write2_b32 v143, v14, v15 offset0:8 offset1:73
	s_waitcnt vmcnt(52)
	ds_write2_b32 v143, v16, v17 offset0:138 offset1:203
	s_waitcnt vmcnt(50)
	ds_write2_b32 v144, v18, v19 offset0:12 offset1:77
	s_waitcnt vmcnt(48)
	ds_write2_b32 v144, v20, v21 offset0:142 offset1:207
	s_waitcnt vmcnt(46)
	ds_write2_b32 v145, v22, v23 offset0:16 offset1:81
	s_waitcnt vmcnt(44)
	ds_write2_b32 v145, v40, v41 offset0:146 offset1:211
	s_waitcnt vmcnt(42)
	ds_write2_b32 v146, v42, v43 offset0:20 offset1:85
	s_waitcnt vmcnt(40)
	ds_write2_b32 v146, v44, v45 offset0:150 offset1:215
	s_waitcnt vmcnt(38)
	ds_write2_b32 v147, v46, v47 offset0:24 offset1:89
	s_waitcnt vmcnt(36)
	ds_write2_b32 v147, v48, v49 offset0:154 offset1:219
	s_waitcnt vmcnt(34)
	ds_write2_b32 v148, v50, v51 offset0:28 offset1:93
	s_waitcnt vmcnt(32)
	ds_write2_b32 v148, v52, v53 offset0:158 offset1:223
	s_waitcnt vmcnt(30)
	ds_write2_b32 v149, v54, v55 offset0:32 offset1:97
	s_waitcnt vmcnt(28)
	ds_write2_b32 v149, v56, v57 offset0:162 offset1:227
	s_waitcnt vmcnt(26)
	ds_write2_b32 v150, v58, v59 offset0:36 offset1:101
	s_waitcnt vmcnt(24)
	ds_write2_b32 v150, v60, v61 offset0:166 offset1:231
	s_waitcnt vmcnt(22)
	ds_write2_b32 v151, v62, v63 offset0:40 offset1:105
	s_waitcnt vmcnt(20)
	ds_write2_b32 v151, v64, v65 offset0:170 offset1:235
	s_waitcnt vmcnt(18)
	ds_write2_b32 v152, v66, v67 offset0:44 offset1:109
	s_waitcnt vmcnt(16)
	ds_write2_b32 v152, v68, v69 offset0:174 offset1:239
	s_waitcnt vmcnt(14)
	ds_write2_b32 v153, v70, v71 offset0:48 offset1:113
	s_waitcnt vmcnt(12)
	ds_write2_b32 v153, v72, v73 offset0:178 offset1:243
	s_waitcnt vmcnt(10)
; #define LAS __attribute__((address_space(3)))
; __device__ __forceinline__ unsigned pk2(float lo, float hi) { return __builtin_bit_cast(unsigned, __builtin_convertvector((f32x2){lo, hi}, bf16x2_t)); }
; #define LDS_WAIT() asm volatile("s_waitcnt lgkmcnt(0)" ::: "memory")
; __device__ __forceinline__ void transpose_item(const float* W, int ldw, bf16_t* WT, int ldt, int koff, int k0, int nsrc, int ndst, LAS float* scr, int lane) {
;     ...
;     for (int kk = 0; kk < 64; ++kk) scr[kk * 65 + lane] = src[(size_t)kk * ldw];
;     LDS_WAIT(); asm volatile("" ::: "memory");
;     const int c = lane & 7;
; #pragma unroll
;     for (int j = 0; j < 8; ++j) { const int n = (lane >> 3) + 8 * j; const LAS float* s = scr + (8 * c) * 65 + n;
;         u32x4 o; o.x = pk2(s[0 * 65], s[1 * 65]); o.y = pk2(s[2 * 65], s[3 * 65]); o.z = pk2(s[4 * 65], s[5 * 65]); o.w = pk2(s[6 * 65], s[7 * 65]);
;         *(u32x4*)((char*)WT + tiled_off_b(ndst + n, koff + k0 + 8 * c)) = o; }
;     LDS_WAIT(); asm volatile("" ::: "memory");
	ds_write2_b32 v154, v74, v75 offset0:52 offset1:117
	s_waitcnt vmcnt(8)
	ds_write2_b32 v154, v76, v36 offset0:182 offset1:247
	s_waitcnt vmcnt(6)
	ds_write2_b32 v155, v37, v24 offset0:56 offset1:121
	s_waitcnt vmcnt(4)
	ds_write2_b32 v155, v25, v26 offset0:186 offset1:251
	s_waitcnt vmcnt(2)
	ds_write2_b32 v156, v27, v28 offset0:60 offset1:125
	s_waitcnt vmcnt(0)
	ds_write2_b32 v156, v29, v4 offset0:190 offset1:255
	s_waitcnt lgkmcnt(0)
	ds_read2_b32 v[8:9], v134 offset0:65 offset1:73
	ds_read2_b32 v[10:11], v134 offset1:8
	ds_read2_b32 v[12:13], v134 offset0:130 offset1:138
	ds_read2_b32 v[14:15], v134 offset0:195 offset1:203
	ds_read2_b32 v[16:17], v157 offset0:4 offset1:12
	ds_read2_b32 v[18:19], v157 offset0:69 offset1:77
	ds_read2_b32 v[20:21], v157 offset0:134 offset1:142
	ds_read2_b32 v[22:23], v157 offset0:199 offset1:207
	s_waitcnt lgkmcnt(0)
	v_cvt_pk_bf16_f32 v4, v10, v8
	v_add_u32_e32 v8, s25, v135
	v_lshrrev_b32_e32 v8, 3, v8
	v_and_or_b32 v8, v8, 10, v131
	v_lshlrev_b32_e32 v8, 10, v8
	v_cvt_pk_bf16_f32 v5, v12, v14
	v_cvt_pk_bf16_f32 v6, v16, v18
	v_cvt_pk_bf16_f32 v7, v20, v22
	v_or_b32_e32 v24, v8, v136
	global_store_dwordx4 v24, v[4:7], s[8:9] nt
	v_or_b32_e32 v25, v8, v137
	v_xor_b32_e32 v24, 32, v24
	v_cvt_pk_bf16_f32 v4, v11, v9
	v_cvt_pk_bf16_f32 v5, v13, v15
	v_cvt_pk_bf16_f32 v6, v17, v19
	v_cvt_pk_bf16_f32 v7, v21, v23
	ds_read2_b32 v[8:9], v134 offset0:16 offset1:24
	ds_read2_b32 v[10:11], v134 offset0:81 offset1:89
	ds_read2_b32 v[12:13], v134 offset0:146 offset1:154
	ds_read2_b32 v[14:15], v134 offset0:211 offset1:219
	ds_read2_b32 v[16:17], v157 offset0:20 offset1:28
	ds_read2_b32 v[18:19], v157 offset0:85 offset1:93
	ds_read2_b32 v[20:21], v157 offset0:150 offset1:158
	ds_read2_b32 v[22:23], v157 offset0:215 offset1:223
	global_store_dwordx4 v25, v[4:7], s[8:9] nt
	v_mov_b32_e32 v25, v3
	v_lshl_add_u64 v[24:25], s[8:9], 0, v[24:25]
	s_waitcnt lgkmcnt(6)
	v_cvt_pk_bf16_f32 v4, v8, v10
	v_add_u32_e32 v8, s25, v133
	v_lshrrev_b32_e32 v8, 3, v8
	v_and_or_b32 v8, v8, 10, v131
	s_waitcnt lgkmcnt(4)
	v_cvt_pk_bf16_f32 v5, v12, v14
	s_waitcnt lgkmcnt(2)
	v_cvt_pk_bf16_f32 v6, v16, v18
	s_waitcnt lgkmcnt(0)
	v_cvt_pk_bf16_f32 v7, v20, v22
	v_lshl_or_b32 v8, v8, 10, v136
	global_store_dwordx4 v[24:25], v[4:7], off offset:512 nt
	v_xor_b32_e32 v8, 32, v8
	v_add_u32_e32 v26, s25, v130
	v_cvt_pk_bf16_f32 v4, v9, v11
	v_mov_b32_e32 v9, v3
	v_cvt_pk_bf16_f32 v5, v13, v15
	v_cvt_pk_bf16_f32 v6, v17, v19
	v_cvt_pk_bf16_f32 v7, v21, v23
	v_lshl_add_u64 v[8:9], s[8:9], 0, v[8:9]
	ds_read2_b32 v[10:11], v134 offset0:32 offset1:40
	ds_read2_b32 v[12:13], v134 offset0:97 offset1:105
	ds_read2_b32 v[14:15], v134 offset0:162 offset1:170
	ds_read2_b32 v[16:17], v134 offset0:227 offset1:235
	ds_read2_b32 v[18:19], v157 offset0:36 offset1:44
	ds_read2_b32 v[20:21], v157 offset0:101 offset1:109
	ds_read2_b32 v[22:23], v157 offset0:166 offset1:174
	ds_read2_b32 v[24:25], v157 offset0:231 offset1:239
	global_store_dwordx4 v[8:9], v[4:7], off offset:768 nt
	v_add_u32_e32 v8, 32, v26
	v_and_or_b32 v9, v8, s74, v135
	v_lshrrev_b32_e32 v9, 3, v9
	v_and_or_b32 v9, v9, 14, v131
	v_lshlrev_b32_e32 v8, 6, v8
	v_and_b32_e32 v8, 0xc0, v8
	v_lshlrev_b32_e32 v9, 10, v9
	s_waitcnt lgkmcnt(6)
	v_cvt_pk_bf16_f32 v4, v10, v12
	s_waitcnt lgkmcnt(4)
	v_cvt_pk_bf16_f32 v5, v14, v16
	s_waitcnt lgkmcnt(2)
	v_cvt_pk_bf16_f32 v6, v18, v20
	s_waitcnt lgkmcnt(0)
	v_cvt_pk_bf16_f32 v7, v22, v24
	v_or3_b32 v8, v9, v8, v132
	global_store_dwordx4 v8, v[4:7], s[8:9] nt
	v_add_u32_e32 v8, 40, v26
	v_and_or_b32 v9, v8, s74, v135
	v_lshrrev_b32_e32 v9, 3, v9
	v_and_or_b32 v9, v9, 14, v131
	v_lshlrev_b32_e32 v8, 6, v8
	v_and_b32_e32 v8, 0xc0, v8
	v_lshlrev_b32_e32 v9, 10, v9
	v_cvt_pk_bf16_f32 v4, v11, v13
	v_cvt_pk_bf16_f32 v5, v15, v17
	v_cvt_pk_bf16_f32 v6, v19, v21
	v_cvt_pk_bf16_f32 v7, v23, v25
	v_or3_b32 v24, v9, v8, v132
	ds_read2_b32 v[8:9], v134 offset0:48 offset1:56
	ds_read2_b32 v[10:11], v134 offset0:113 offset1:121
	ds_read2_b32 v[12:13], v134 offset0:178 offset1:186
	ds_read2_b32 v[14:15], v134 offset0:243 offset1:251
	ds_read2_b32 v[16:17], v157 offset0:52 offset1:60
	ds_read2_b32 v[18:19], v157 offset0:117 offset1:125
	ds_read2_b32 v[20:21], v157 offset0:182 offset1:190
	ds_read2_b32 v[22:23], v157 offset0:247 offset1:255
	global_store_dwordx4 v24, v[4:7], s[8:9] offset:256 nt
	v_mov_b32_e32 v25, v3
	s_waitcnt lgkmcnt(6)
	v_cvt_pk_bf16_f32 v4, v8, v10
	v_add_u32_e32 v8, 48, v26
	v_and_or_b32 v10, v8, s74, v135
	v_lshrrev_b32_e32 v10, 3, v10
	v_and_or_b32 v10, v10, 14, v131
	v_lshlrev_b32_e32 v8, 6, v8
	v_and_b32_e32 v8, 0xc0, v8
	v_lshlrev_b32_e32 v10, 10, v10
	v_or3_b32 v8, v10, v8, v132
	v_xor_b32_e32 v24, 32, v8
	s_waitcnt lgkmcnt(4)
	v_cvt_pk_bf16_f32 v5, v12, v14
	s_waitcnt lgkmcnt(2)
	v_cvt_pk_bf16_f32 v6, v16, v18
	s_waitcnt lgkmcnt(0)
	v_cvt_pk_bf16_f32 v7, v20, v22
	v_lshl_add_u64 v[24:25], s[8:9], 0, v[24:25]
	v_add_u32_e32 v8, 56, v26
	global_store_dwordx4 v[24:25], v[4:7], off offset:512 nt
	s_nop 1
	v_cvt_pk_bf16_f32 v4, v9, v11
	v_and_or_b32 v9, v8, s74, v133
	v_lshrrev_b32_e32 v9, 3, v9
	v_and_or_b32 v9, v9, 14, v131
	v_lshlrev_b32_e32 v8, 6, v8
	v_and_b32_e32 v8, 0xc0, v8
	v_lshlrev_b32_e32 v9, 10, v9
	v_or3_b32 v8, v9, v8, v132
	v_xor_b32_e32 v8, 32, v8
	v_mov_b32_e32 v9, v3
	v_cvt_pk_bf16_f32 v5, v13, v15
	v_cvt_pk_bf16_f32 v6, v17, v19
	v_cvt_pk_bf16_f32 v7, v21, v23
	v_lshl_add_u64 v[8:9], s[8:9], 0, v[8:9]
	global_store_dwordx4 v[8:9], v[4:7], off offset:768 nt
	s_waitcnt lgkmcnt(0)
